# v3 + dead zero-movs removed, row-sum init folded into first adds (A and B NOMAX loops)
# speedup vs baseline: 1.0030x; 1.0030x over previous
; #define SBAR() __builtin_amdgcn_sched_barrier(0)
; __device__ __forceinline__ s16x4 vtr(lds_cptr p) { return __builtin_bit_cast(s16x4, __builtin_amdgcn_ds_read_tr16_b64_v4i16((__attribute__((address_space(3))) v4i16_t*)p)); }
; #define PIN(x) asm volatile("" : "+v"(x))
; __device__ __forceinline__ void add_bias(f32x16& p0, f32x16& p1, const float* tb, int relb, int hi) {
;   const float* t = tb + relb + 4 * hi;
; #pragma unroll
;   for (int r = 0; r < 16; ++r) { p0[r] += t[(r & 3) + 8 * (r >> 2)]; p1[r] += t[32 + (r & 3) + 8 * (r >> 2)]; }
; template <int DK, bool NOMAX> ...
;     ...
;   float psa = 0.f, psb = 0.f;
;   SBAR();
; #pragma unroll
;   for (int d0 = 0; d0 < NS; ++d0) {
;     if (d0 == 0) { c0 = __builtin_amdgcn_mfma_f32_32x32x16_bf16(kf[0][0], qr[0], f32x16{}, 0, 0, 0); c1 = __builtin_amdgcn_mfma_f32_32x32x16_bf16(kf[0][1], qr[0], f32x16{}, 0, 0, 0); }
;     else { c0 = __builtin_amdgcn_mfma_f32_32x32x16_bf16(kf[d0 & 1][0], qr[d0], c0, 0, 0, 0); c1 = __builtin_amdgcn_mfma_f32_32x32x16_bf16(kf[d0 & 1][1], qr[d0], c1, 0, 0, 0); }
;     if (d0 + 2 < NS) KRD_(d0 & 1, d0 + 2);
;     if constexpr (NOMAX) { }
;     else {
; #pragma unroll
;     for (int r = d0 * RPS; r < (d0 + 1) * RPS; ++r) { p1[r] = __builtin_amdgcn_exp2f(p1[r]); psa += p0[r]; }
;     if (d0 > 0) {
; #pragma unroll
;       for (int r = (d0 - 1) * RPS; r < d0 * RPS; ++r) psb += p1[r]; } }
;     if constexpr (NOMAX) {
;       if (d0 == NS / 4 - 1) { PK4R(p0, 0, pa[0]); PIN(pa[0]); }
;       if (d0 == NS / 2 - 1) { PK4R(p0, 8, pa[1]); PIN(pa[1]); }
;       if (d0 == 3 * NS / 4 - 1) { PK4R(p1, 0, pa[2]); PIN(pa[2]); }
;       if (d0 == NS - 1) { PK4R(p1, 8, pa[3]); PIN(pa[3]); }
;     } else {
;     if (d0 == NS / 2 - 1) { PK4R(p0, 0, pa[0]); PIN(pa[0]); }
;     if (d0 == NS / 2) { PK4R(p0, 8, pa[1]); PIN(pa[1]); }
;     if (d0 == NS - 1) { PK4R(p1, 0, pa[2]); PIN(pa[2]); }
;     }
;     if (d0 == NS - 1) {
;       vl[0] = vtr(vp + v_rd_off(0, 0, 0)); vh[0] = vtr(vp + v_rd_off(0, 0, 1)); vl[1] = vtr(vp + v_rd_off(1, 0, 0)); vh[1] = vtr(vp + v_rd_off(1, 0, 1)); }
;     PIN(p1); PIN(psa); PIN(psb);
;     SBAR();
;   }
.LBB0_220:
	s_mov_b32 s6, s96
	s_mov_b32 s96, s4
	s_add_i32 s4, s63, 0xffff4000
	s_and_b32 s59, s4, 0xc000
	s_add_i32 s4, s59, 0
	v_add_u32_e32 v213, s96, v187
	s_waitcnt lgkmcnt(0)
	v_mfma_f32_32x32x16_bf16 v[128:143], v[116:119], v[156:159], 0
	v_add_u32_e32 v0, s4, v207
	ds_read_b128 v[2:5], v0
	ds_read_b128 v[164:167], v0 offset:4096
	v_cvt_pk_bf16_f32 v96, v96, v97
	v_cvt_pk_bf16_f32 v97, v98, v99
	v_cvt_pk_bf16_f32 v98, v100, v101
	v_cvt_pk_bf16_f32 v99, v102, v103
	v_mfma_f32_32x32x16_bf16 v[112:127], v[112:115], v[156:159], 0
	v_permlane32_swap_b32_e32 v96, v98
	v_permlane32_swap_b32_e32 v97, v99
	v_mfma_f32_32x32x16_bf16 v[128:143], v[10:13], v[152:155], v[128:143]
	v_mfma_f32_32x32x16_bf16 v[112:127], v[6:9], v[152:155], v[112:127]
	v_add_u32_e32 v6, s4, v208
	ds_read_b128 v[100:103], v6
	ds_read_b128 v[214:217], v6 offset:4096
	v_cvt_pk_bf16_f32 v10, v104, v105
	v_cvt_pk_bf16_f32 v11, v106, v107
	v_cvt_pk_bf16_f32 v12, v108, v109
	v_cvt_pk_bf16_f32 v13, v110, v111
	s_nop 0
	v_permlane32_swap_b32_e32 v10, v12
	v_permlane32_swap_b32_e32 v11, v13
	s_waitcnt lgkmcnt(3)
	v_mfma_f32_32x32x16_bf16 v[128:143], v[2:5], v[148:151], v[128:143]
	v_cvt_pk_bf16_f32 v6, v80, v81
	v_cvt_pk_bf16_f32 v7, v82, v83
	v_cvt_pk_bf16_f32 v8, v84, v85
	v_cvt_pk_bf16_f32 v9, v86, v87
	s_nop 0
	v_permlane32_swap_b32_e32 v6, v8
	s_waitcnt lgkmcnt(2)
	v_mfma_f32_32x32x16_bf16 v[112:127], v[164:167], v[148:151], v[112:127]
	v_permlane32_swap_b32_e32 v7, v9
	s_nop 0
	v_cvt_pk_bf16_f32 v2, v88, v89
	v_cvt_pk_bf16_f32 v3, v90, v91
	v_cvt_pk_bf16_f32 v4, v92, v93
	v_cvt_pk_bf16_f32 v5, v94, v95
	s_waitcnt lgkmcnt(1)
	v_mfma_f32_32x32x16_bf16 v[128:143], v[100:103], v[144:147], v[128:143]
	v_permlane32_swap_b32_e32 v2, v4
	v_permlane32_swap_b32_e32 v3, v5
	ds_read_b64_tr_b16 v[104:105], v213
	ds_read_b64_tr_b16 v[106:107], v213 offset:2048
	ds_read_b64_tr_b16 v[100:101], v213 offset:512
	ds_read_b64_tr_b16 v[102:103], v213 offset:2560
	s_waitcnt lgkmcnt(4)
	v_mfma_f32_32x32x16_bf16 v[112:127], v[214:217], v[144:147], v[112:127]
	v_add_u32_e32 v216, s7, v205
	v_add_u32_e32 v0, 0xffffffa1, v216
	v_cmp_gt_i32_e32 vcc, s67, v0
	v_mov_b32_e32 v215, v199
	s_and_saveexec_b64 s[4:5], vcc
	s_cbranch_execz .LBB0_224
	v_subrev_u32_e32 v0, 64, v216
	v_cmp_lt_i32_e32 vcc, s77, v0
	v_mov_b32_e32 v215, v198
	s_and_saveexec_b64 s[18:19], vcc
	s_cbranch_execz .LBB0_223
	ds_read2_b32 v[80:81], v211 offset1:1
	ds_read2_b32 v[82:83], v211 offset0:2 offset1:3
	ds_read2_b32 v[84:85], v211 offset0:8 offset1:9
	ds_read2_b32 v[86:87], v211 offset0:10 offset1:11
	ds_read2_b32 v[88:89], v211 offset0:16 offset1:17
	ds_read2_b32 v[90:91], v211 offset0:18 offset1:19
	ds_read2_b32 v[92:93], v211 offset0:24 offset1:25
	ds_read2_b32 v[94:95], v211 offset0:26 offset1:27
	ds_read2_b32 v[108:109], v211 offset0:32 offset1:33
	ds_read2_b32 v[110:111], v211 offset0:34 offset1:35
	ds_read2_b32 v[164:165], v211 offset0:40 offset1:41
	ds_read2_b32 v[166:167], v211 offset0:42 offset1:43
	s_waitcnt lgkmcnt(0)
	v_pk_add_f32 v[128:129], v[128:129], v[80:81]
	v_pk_add_f32 v[140:141], v[140:141], v[92:93]
	v_pk_add_f32 v[138:139], v[138:139], v[90:91]
	v_pk_add_f32 v[136:137], v[136:137], v[88:89]
	ds_read2_b32 v[80:81], v211 offset0:48 offset1:49
	ds_read2_b32 v[88:89], v211 offset0:50 offset1:51
	ds_read2_b32 v[90:91], v211 offset0:56 offset1:57
	ds_read2_b32 v[92:93], v211 offset0:58 offset1:59
	v_pk_add_f32 v[142:143], v[142:143], v[94:95]
	v_pk_add_f32 v[134:135], v[134:135], v[86:87]
	v_pk_add_f32 v[132:133], v[132:133], v[84:85]
	v_pk_add_f32 v[130:131], v[130:131], v[82:83]
	v_pk_add_f32 v[112:113], v[112:113], v[108:109]
	s_waitcnt lgkmcnt(0)
	v_pk_add_f32 v[126:127], v[126:127], v[92:93]
	v_pk_add_f32 v[124:125], v[124:125], v[90:91]
	v_pk_add_f32 v[122:123], v[122:123], v[88:89]
	v_pk_add_f32 v[120:121], v[120:121], v[80:81]
	v_pk_add_f32 v[118:119], v[118:119], v[166:167]
	v_pk_add_f32 v[116:117], v[116:117], v[164:165]
	v_pk_add_f32 v[114:115], v[114:115], v[110:111]
	v_mov_b32_e32 v215, 0

; #define SBAR() __builtin_amdgcn_sched_barrier(0)
; #define PIN(x) asm volatile("" : "+v"(x))
; #define VRD_(S, I) do { vl[S] = vtr(vp + v_rd_off((I) & 3, (I) >> 2, 0)); vh[S] = vtr(vp + v_rd_off((I) & 3, (I) >> 2, 1)); } while (0)
; template <int DK, bool NOMAX> ...
;     ...
; #pragma unroll
;   for (int i = 0; i < 16; ++i) {
;     if (i + 2 < 16) VRD_((i + 2) % 3, i + 2);
;     if (i == 1) { if (dk) __builtin_amdgcn_global_load_lds((const unsigned*)gk0, lk, 16, 0, 0); }
;     if (i == 3) { if constexpr (DK == 128) { if (dk) __builtin_amdgcn_global_load_lds((const unsigned*)gk1, (lds_up)((lds_cp)lk + 8192), 16, 0, 0); } }
;     if (i == 5) { if (dv) __builtin_amdgcn_global_load_lds((const unsigned*)gv0, lv, 16, 0, 0); }
;     if (i == 7) { if (dv) __builtin_amdgcn_global_load_lds((const unsigned*)gv1, (lds_up)((lds_cp)lv + 8192), 16, 0, 0); }
;     if (i == 12 || i == 13) { const int cb_ = ((i - 12) * 16 + hi * 8) * 2;
;       if constexpr (DK == 128) { kf[i - 12][0] = *reinterpret_cast<const bf16x8*>(Kn + KSWZ128(r32, cb_)); kf[i - 12][1] = *reinterpret_cast<const bf16x8*>(Kn + KSWZ128(32 + r32, cb_)); }
;       else { kf[i - 12][0] = *reinterpret_cast<const bf16x8*>(Kn + KSWZ64(r32, cb_)); kf[i - 12][1] = *reinterpret_cast<const bf16x8*>(Kn + KSWZ64(32 + r32, cb_)); } }
;     SBAR();
;     o[i & 3] = __builtin_amdgcn_mfma_f32_32x32x16_bf16(pa[i >> 2], VFR_(i % 3), o[i & 3], 0, 0, 0);
;     if constexpr (NOMAX) { c0[i] = __builtin_amdgcn_exp2f(c0[i]); c1[i] = __builtin_amdgcn_exp2f(c1[i]); if (i > 0) { psa += c0[i - 1]; psb += c1[i - 1]; } PIN(c0); PIN(c1); PIN(psa); PIN(psb); }
.LBB0_224:
	s_or_b64 exec, exec, s[4:5]
	s_add_i32 s97, s97, 2
	s_cmpk_gt_u32 s97, 0x7c
	s_cselect_b64 s[18:19], -1, 0
	ds_read_b64_tr_b16 v[80:81], v213 offset:1024
	ds_read_b64_tr_b16 v[82:83], v213 offset:3072
	s_waitcnt lgkmcnt(4)
	v_mfma_f32_32x32x16_bf16 v[16:31], v[96:99], v[104:107], v[16:31]
	v_exp_f32_e32 v128, v128
	v_exp_f32_e32 v112, v112
	ds_read_b64_tr_b16 v[84:85], v213 offset:1536
	ds_read_b64_tr_b16 v[86:87], v213 offset:3584
	s_and_b64 vcc, exec, s[18:19]
	v_lshl_add_u64 v[164:165], s[0:1], 0, v[162:163]
	s_cbranch_vccnz .LBB0_226
	s_and_b32 s4, s63, 0xc000
	v_lshl_add_u64 v[90:91], v[164:165], 0, s[28:29]
	s_add_i32 m0, s3, s4
	s_nop 0
	global_load_lds_dwordx4 v[90:91], off
; template <int DK, bool NOMAX> ...
;     ...
; #pragma unroll
;   for (int i = 0; i < 16; ++i) {
;     if (i + 2 < 16) VRD_((i + 2) % 3, i + 2);
;     if (i == 1) { if (dk) __builtin_amdgcn_global_load_lds((const unsigned*)gk0, lk, 16, 0, 0); }
;     if (i == 3) { if constexpr (DK == 128) { if (dk) __builtin_amdgcn_global_load_lds((const unsigned*)gk1, (lds_up)((lds_cp)lk + 8192), 16, 0, 0); } }
;     if (i == 5) { if (dv) __builtin_amdgcn_global_load_lds((const unsigned*)gv0, lv, 16, 0, 0); }
;     if (i == 7) { if (dv) __builtin_amdgcn_global_load_lds((const unsigned*)gv1, (lds_up)((lds_cp)lv + 8192), 16, 0, 0); }
;     if (i == 12 || i == 13) { const int cb_ = ((i - 12) * 16 + hi * 8) * 2;
;       if constexpr (DK == 128) { kf[i - 12][0] = *reinterpret_cast<const bf16x8*>(Kn + KSWZ128(r32, cb_)); kf[i - 12][1] = *reinterpret_cast<const bf16x8*>(Kn + KSWZ128(32 + r32, cb_)); }
;       else { kf[i - 12][0] = *reinterpret_cast<const bf16x8*>(Kn + KSWZ64(r32, cb_)); kf[i - 12][1] = *reinterpret_cast<const bf16x8*>(Kn + KSWZ64(32 + r32, cb_)); } }
;     SBAR();
;     o[i & 3] = __builtin_amdgcn_mfma_f32_32x32x16_bf16(pa[i >> 2], VFR_(i % 3), o[i & 3], 0, 0, 0);
;     if constexpr (NOMAX) { c0[i] = __builtin_amdgcn_exp2f(c0[i]); c1[i] = __builtin_amdgcn_exp2f(c1[i]); if (i > 0) { psa += c0[i - 1]; psb += c1[i - 1]; } PIN(c0); PIN(c1); PIN(psa); PIN(psb); }
;     else {
;     if (i == 0) { ma = max3f(c0[0], c0[1], c1[0]); mb = max3f(c0[2], c0[3], c1[1]); ma = max3f(ma, c1[2], c1[3]); }
;     if (i >= 1 && i <= 3) { const int r = 4 * i; ma = max3f(ma, c0[r], c0[r + 1]); mb = max3f(mb, c0[r + 2], c0[r + 3]); ma = max3f(ma, c1[r], c1[r + 1]); mb = max3f(mb, c1[r + 2], c1[r + 3]); }
;     if (i == 4) { float pmax = fmaxf(ma, mb);
;       { auto rr = __builtin_amdgcn_permlane32_swap(__float_as_uint(pmax), __float_as_uint(pmax), false, false);
;         pmax = fmaxf(__uint_as_float(rr[0]), __uint_as_float(rr[1])); }
;       pmax += cb;
;       const bool keep = __all(pmax - m_reg <= THR2);
;       const float mn = keep ? m_reg : fmaxf(m_reg, pmax);
;       alpha = __builtin_amdgcn_exp2f(m_reg - mn); m_reg = mn; mnC = cb - mn; }
;     if (i >= 5 && i <= 8) { const int r = 4 * (i - 5);
; #pragma unroll
;       for (int q = 0; q < 4; ++q) { c0[r + q] += mnC; c1[r + q] += mnC; } }
;     if (i >= 9) { const int r0 = (i - 9) * 2 + (i > 14 ? 1 : 0), n = i >= 14 ? 3 : 2;
.LBB0_226:
	v_sub_f32_e32 v0, v212, v215
	v_exp_f32_e32 v0, v0
	s_add_i32 s4, s63, 0xffff8000
	s_and_b32 s4, s4, 0xc000
	s_add_i32 s94, s4, 0
	v_lshl_add_u64 v[166:167], s[0:1], 0, v[160:161]
	v_lshl_add_u64 v[168:169], s[0:1], 0, v[14:15]
	v_lshl_add_u64 v[92:93], v[166:167], 0, s[30:31]
	v_lshl_add_u64 v[94:95], v[168:169], 0, s[30:31]
	s_waitcnt lgkmcnt(4)
	v_mfma_f32_32x32x16_bf16 v[32:47], v[96:99], v[100:103], v[32:47]
	v_exp_f32_e32 v129, v129
	v_exp_f32_e32 v113, v113
	ds_read_b64_tr_b16 v[88:89], v213 offset:4096
	ds_read_b64_tr_b16 v[90:91], v213 offset:6144
	s_waitcnt lgkmcnt(4)
	v_mfma_f32_32x32x16_bf16 v[48:63], v[96:99], v[80:83], v[48:63]
	v_exp_f32_e32 v130, v130
	v_exp_f32_e32 v114, v114
	v_add_f32_e32 v100, v113, v112
	v_add_f32_e32 v101, v129, v128
	ds_read_b64_tr_b16 v[80:81], v213 offset:4608
	ds_read_b64_tr_b16 v[82:83], v213 offset:6656
	s_waitcnt lgkmcnt(4)
	v_mfma_f32_32x32x16_bf16 v[64:79], v[96:99], v[84:87], v[64:79]
	v_exp_f32_e32 v131, v131
	v_exp_f32_e32 v115, v115
	v_add_f32_e32 v96, v114, v100
	v_add_f32_e32 v97, v130, v101
	ds_read_b64_tr_b16 v[84:85], v213 offset:5120
	ds_read_b64_tr_b16 v[86:87], v213 offset:7168
	s_waitcnt lgkmcnt(4)
	v_mfma_f32_32x32x16_bf16 v[16:31], v[10:13], v[88:91], v[16:31]
	v_exp_f32_e32 v132, v132
	v_exp_f32_e32 v116, v116
	v_add_f32_e32 v96, v115, v96
	v_add_f32_e32 v97, v131, v97
	s_add_i32 s4, s62, s58
	s_mov_b32 m0, s4
	ds_read_b64_tr_b16 v[88:89], v213 offset:5632
	ds_read_b64_tr_b16 v[90:91], v213 offset:7680
	global_load_lds_dwordx4 v[92:93], off
	s_waitcnt lgkmcnt(4)
	v_mfma_f32_32x32x16_bf16 v[32:47], v[10:13], v[80:83], v[32:47]
	v_exp_f32_e32 v133, v133
	v_exp_f32_e32 v117, v117
	v_add_f32_e32 v92, v116, v96
	v_add_f32_e32 v93, v132, v97
	ds_read_b64_tr_b16 v[80:81], v213 offset:8192
	ds_read_b64_tr_b16 v[82:83], v213 offset:10240
	s_waitcnt lgkmcnt(4)
	v_mfma_f32_32x32x16_bf16 v[48:63], v[10:13], v[84:87], v[48:63]
	v_exp_f32_e32 v134, v134
	v_exp_f32_e32 v118, v118
	v_add_f32_e32 v92, v117, v92
	v_add_f32_e32 v93, v133, v93
	s_add_i32 m0, s4, 0x2000
	ds_read_b64_tr_b16 v[84:85], v213 offset:8704
	ds_read_b64_tr_b16 v[86:87], v213 offset:10752
	global_load_lds_dwordx4 v[94:95], off
	s_waitcnt lgkmcnt(4)
	v_mfma_f32_32x32x16_bf16 v[64:79], v[10:13], v[88:91], v[64:79]
	v_exp_f32_e32 v135, v135
	v_exp_f32_e32 v119, v119
	v_add_f32_e32 v88, v118, v92
	v_add_f32_e32 v89, v134, v93
	ds_read_b64_tr_b16 v[10:11], v213 offset:9216
	ds_read_b64_tr_b16 v[12:13], v213 offset:11264
	s_waitcnt lgkmcnt(4)
	v_mfma_f32_32x32x16_bf16 v[16:31], v[6:9], v[80:83], v[16:31]
	v_exp_f32_e32 v136, v136
	v_exp_f32_e32 v120, v120
	v_add_f32_e32 v88, v119, v88
	v_add_f32_e32 v89, v135, v89
	ds_read_b64_tr_b16 v[80:81], v213 offset:9728
	ds_read_b64_tr_b16 v[82:83], v213 offset:11776
	s_waitcnt lgkmcnt(4)
	v_mfma_f32_32x32x16_bf16 v[32:47], v[6:9], v[84:87], v[32:47]
	v_exp_f32_e32 v137, v137
	v_exp_f32_e32 v121, v121
	v_add_f32_e32 v84, v120, v88
	v_add_f32_e32 v85, v136, v89
	ds_read_b64_tr_b16 v[88:89], v213 offset:12288
	ds_read_b64_tr_b16 v[90:91], v213 offset:14336
	s_waitcnt lgkmcnt(4)
	v_mfma_f32_32x32x16_bf16 v[48:63], v[6:9], v[10:13], v[48:63]
	v_exp_f32_e32 v138, v138
	v_exp_f32_e32 v122, v122
	v_add_f32_e32 v10, v121, v84
	v_add_f32_e32 v11, v137, v85
	ds_read_b64_tr_b16 v[92:93], v213 offset:12800
	ds_read_b64_tr_b16 v[94:95], v213 offset:14848
	s_waitcnt lgkmcnt(4)
	v_mfma_f32_32x32x16_bf16 v[64:79], v[6:9], v[80:83], v[64:79]
	v_exp_f32_e32 v139, v139
	v_exp_f32_e32 v123, v123
	v_add_f32_e32 v6, v122, v10
	v_add_f32_e32 v7, v138, v11
	v_add_u32_e32 v8, s94, v209
	ds_read_b64_tr_b16 v[96:97], v213 offset:13312
	ds_read_b64_tr_b16 v[98:99], v213 offset:15360
	ds_read_b128 v[80:83], v8
	ds_read_b128 v[84:87], v8 offset:4096
	s_waitcnt lgkmcnt(6)
	v_mfma_f32_32x32x16_bf16 v[16:31], v[2:5], v[88:91], v[16:31]
	v_exp_f32_e32 v140, v140
	v_exp_f32_e32 v124, v124
	v_add_f32_e32 v100, v123, v6
	v_add_f32_e32 v101, v139, v7
	v_add_u32_e32 v10, s94, v210
	ds_read_b64_tr_b16 v[88:89], v213 offset:13824
	ds_read_b64_tr_b16 v[90:91], v213 offset:15872
	ds_read_b128 v[6:9], v10
	ds_read_b128 v[10:13], v10 offset:4096
	s_waitcnt lgkmcnt(8)
	v_mfma_f32_32x32x16_bf16 v[32:47], v[2:5], v[92:95], v[32:47]
	v_exp_f32_e32 v141, v141
	v_exp_f32_e32 v125, v125
	v_add_f32_e32 v92, v124, v100
	v_add_f32_e32 v93, v140, v101
	s_waitcnt lgkmcnt(6)
	v_mfma_f32_32x32x16_bf16 v[48:63], v[2:5], v[96:99], v[48:63]
	v_exp_f32_e32 v142, v142
	v_exp_f32_e32 v126, v126
	v_add_f32_e32 v92, v125, v92
	v_add_f32_e32 v93, v141, v93
	s_waitcnt lgkmcnt(2)
	v_mfma_f32_32x32x16_bf16 v[64:79], v[2:5], v[88:91], v[64:79]
	v_exp_f32_e32 v143, v143
	v_exp_f32_e32 v127, v127
	v_add_f32_e32 v2, v126, v92
	v_add_f32_e32 v3, v142, v93
	s_nop 0
	v_add_f32_e32 v3, v143, v3
	v_add_f32_e32 v2, v127, v2
	v_add_f32_e32 v213, v3, v2
	v_mov_b32_e32 v214, v213
	s_nop 1
	v_permlane32_swap_b32_e32 v213, v214
	v_cmp_neq_f32_e32 vcc, 1.0, v0
	s_cbranch_vccz .LBB0_230
	s_and_saveexec_b64 s[4:5], s[46:47]
	ds_write_b32 v188, v0 offset:128
	s_or_b64 exec, exec, s[4:5]
	s_waitcnt lgkmcnt(0)
	v_add_u32_e32 v96, s2, v171
	ds_read_b128 v[2:5], v96 offset:224
	ds_read_b128 v[88:91], v96 offset:192
	ds_read_b128 v[92:95], v96 offset:160
	ds_read_b128 v[96:99], v96 offset:128
	s_waitcnt lgkmcnt(0)
	v_pk_mul_f32 v[28:29], v[28:29], v[2:3]
	v_pk_mul_f32 v[24:25], v[24:25], v[88:89]
	v_pk_mul_f32 v[20:21], v[20:21], v[92:93]
	v_pk_mul_f32 v[30:31], v[30:31], v[4:5]
	v_pk_mul_f32 v[26:27], v[26:27], v[90:91]
	v_pk_mul_f32 v[22:23], v[22:23], v[94:95]
	v_pk_mul_f32 v[18:19], v[18:19], v[98:99]
	v_pk_mul_f32 v[16:17], v[16:17], v[96:97]
	v_pk_mul_f32 v[44:45], v[44:45], v[2:3]
	v_pk_mul_f32 v[40:41], v[40:41], v[88:89]
	v_pk_mul_f32 v[36:37], v[36:37], v[92:93]
	v_pk_mul_f32 v[46:47], v[46:47], v[4:5]
	v_pk_mul_f32 v[42:43], v[42:43], v[90:91]
	v_pk_mul_f32 v[38:39], v[38:39], v[94:95]
	v_pk_mul_f32 v[34:35], v[34:35], v[98:99]
	v_pk_mul_f32 v[32:33], v[32:33], v[96:97]
	v_pk_mul_f32 v[60:61], v[60:61], v[2:3]
	v_pk_mul_f32 v[56:57], v[56:57], v[88:89]
	v_pk_mul_f32 v[52:53], v[52:53], v[92:93]
	v_pk_mul_f32 v[62:63], v[62:63], v[4:5]
	v_pk_mul_f32 v[58:59], v[58:59], v[90:91]
	v_pk_mul_f32 v[54:55], v[54:55], v[94:95]
	v_pk_mul_f32 v[50:51], v[50:51], v[98:99]
	v_pk_mul_f32 v[48:49], v[48:49], v[96:97]
	v_pk_mul_f32 v[76:77], v[76:77], v[2:3]
	v_pk_mul_f32 v[72:73], v[72:73], v[88:89]
	v_pk_mul_f32 v[68:69], v[68:69], v[92:93]
	v_pk_mul_f32 v[78:79], v[78:79], v[4:5]
	v_pk_mul_f32 v[74:75], v[74:75], v[90:91]
	v_pk_mul_f32 v[70:71], v[70:71], v[94:95]
	v_pk_mul_f32 v[66:67], v[66:67], v[98:99]
	v_pk_mul_f32 v[64:65], v[64:65], v[96:97]

; #define SBAR() __builtin_amdgcn_sched_barrier(0)
; __device__ __forceinline__ s16x4 vtr(lds_cptr p) { return __builtin_bit_cast(s16x4, __builtin_amdgcn_ds_read_tr16_b64_v4i16((__attribute__((address_space(3))) v4i16_t*)p)); }
; #define PIN(x) asm volatile("" : "+v"(x))
; __device__ __forceinline__ void add_bias(f32x16& p0, f32x16& p1, const float* tb, int relb, int hi) {
;   const float* t = tb + relb + 4 * hi;
; #pragma unroll
;   for (int r = 0; r < 16; ++r) { p0[r] += t[(r & 3) + 8 * (r >> 2)]; p1[r] += t[32 + (r & 3) + 8 * (r >> 2)]; }
; template <int DK, bool NOMAX> ...
;     ...
;   float psa = 0.f, psb = 0.f;
;   SBAR();
; #pragma unroll
;   for (int d0 = 0; d0 < NS; ++d0) {
;     if (d0 == 0) { c0 = __builtin_amdgcn_mfma_f32_32x32x16_bf16(kf[0][0], qr[0], f32x16{}, 0, 0, 0); c1 = __builtin_amdgcn_mfma_f32_32x32x16_bf16(kf[0][1], qr[0], f32x16{}, 0, 0, 0); }
;     else { c0 = __builtin_amdgcn_mfma_f32_32x32x16_bf16(kf[d0 & 1][0], qr[d0], c0, 0, 0, 0); c1 = __builtin_amdgcn_mfma_f32_32x32x16_bf16(kf[d0 & 1][1], qr[d0], c1, 0, 0, 0); }
;     if (d0 + 2 < NS) KRD_(d0 & 1, d0 + 2);
;     if constexpr (NOMAX) { }
;     else {
; #pragma unroll
;     for (int r = d0 * RPS; r < (d0 + 1) * RPS; ++r) { p1[r] = __builtin_amdgcn_exp2f(p1[r]); psa += p0[r]; }
;     if (d0 > 0) {
; #pragma unroll
;       for (int r = (d0 - 1) * RPS; r < d0 * RPS; ++r) psb += p1[r]; } }
;     if constexpr (NOMAX) {
;       if (d0 == NS / 4 - 1) { PK4R(p0, 0, pa[0]); PIN(pa[0]); }
;       if (d0 == NS / 2 - 1) { PK4R(p0, 8, pa[1]); PIN(pa[1]); }
;       if (d0 == 3 * NS / 4 - 1) { PK4R(p1, 0, pa[2]); PIN(pa[2]); }
;       if (d0 == NS - 1) { PK4R(p1, 8, pa[3]); PIN(pa[3]); }
;     } else {
;     if (d0 == NS / 2 - 1) { PK4R(p0, 0, pa[0]); PIN(pa[0]); }
;     if (d0 == NS / 2) { PK4R(p0, 8, pa[1]); PIN(pa[1]); }
;     if (d0 == NS - 1) { PK4R(p1, 0, pa[2]); PIN(pa[2]); }
;     }
;     if (d0 == NS - 1) {
;       vl[0] = vtr(vp + v_rd_off(0, 0, 0)); vh[0] = vtr(vp + v_rd_off(0, 0, 1)); vl[1] = vtr(vp + v_rd_off(1, 0, 0)); vh[1] = vtr(vp + v_rd_off(1, 0, 1)); }
;     PIN(p1); PIN(psa); PIN(psb);
;     SBAR();
;   }
.LBB0_234:
	v_add_u32_e32 v217, s6, v187
	v_mfma_f32_32x32x16_bf16 v[96:111], v[80:83], v[156:159], 0
	v_add_u32_e32 v212, s94, v207
	ds_read_b128 v[2:5], v212
	ds_read_b128 v[218:221], v212 offset:4096
	v_cvt_pk_bf16_f32 v128, v128, v129
	v_cvt_pk_bf16_f32 v129, v130, v131
	v_cvt_pk_bf16_f32 v130, v132, v133
	v_cvt_pk_bf16_f32 v131, v134, v135
	v_mfma_f32_32x32x16_bf16 v[80:95], v[84:87], v[156:159], 0
	v_permlane32_swap_b32_e32 v128, v130
	v_permlane32_swap_b32_e32 v129, v131
	v_mfma_f32_32x32x16_bf16 v[96:111], v[6:9], v[152:155], v[96:111]
	v_add_u32_e32 v6, s94, v208
	ds_read_b128 v[132:135], v6
	ds_read_b128 v[222:225], v6 offset:4096
	v_mfma_f32_32x32x16_bf16 v[80:95], v[10:13], v[152:155], v[80:95]
	v_cvt_pk_bf16_f32 v10, v136, v137
	v_cvt_pk_bf16_f32 v11, v138, v139
	v_cvt_pk_bf16_f32 v12, v140, v141
	v_cvt_pk_bf16_f32 v13, v142, v143
	s_nop 0
	v_permlane32_swap_b32_e32 v10, v12
	v_permlane32_swap_b32_e32 v11, v13
	s_waitcnt lgkmcnt(3)
	v_mfma_f32_32x32x16_bf16 v[96:111], v[2:5], v[148:151], v[96:111]
	v_cvt_pk_bf16_f32 v6, v112, v113
	v_cvt_pk_bf16_f32 v7, v114, v115
	v_cvt_pk_bf16_f32 v8, v116, v117
	v_cvt_pk_bf16_f32 v9, v118, v119
	s_nop 0
	v_permlane32_swap_b32_e32 v6, v8
	s_waitcnt lgkmcnt(2)
	v_mfma_f32_32x32x16_bf16 v[80:95], v[218:221], v[148:151], v[80:95]
	v_permlane32_swap_b32_e32 v7, v9
	s_nop 0
	v_cvt_pk_bf16_f32 v2, v120, v121
	v_cvt_pk_bf16_f32 v3, v122, v123
	v_cvt_pk_bf16_f32 v4, v124, v125
	v_cvt_pk_bf16_f32 v5, v126, v127
	s_waitcnt lgkmcnt(1)
	v_mfma_f32_32x32x16_bf16 v[96:111], v[132:135], v[144:147], v[96:111]
	v_permlane32_swap_b32_e32 v2, v4
	v_permlane32_swap_b32_e32 v3, v5
	ds_read_b64_tr_b16 v[136:137], v217
	ds_read_b64_tr_b16 v[138:139], v217 offset:2048
	ds_read_b64_tr_b16 v[132:133], v217 offset:512
	ds_read_b64_tr_b16 v[134:135], v217 offset:2560
	s_waitcnt lgkmcnt(4)
	v_mfma_f32_32x32x16_bf16 v[80:95], v[222:225], v[144:147], v[80:95]
	v_subrev_u32_e32 v112, 31, v216
	v_cmp_gt_i32_e32 vcc, s67, v112
	v_mov_b32_e32 v212, v199
	s_and_saveexec_b64 s[4:5], vcc
	s_cbranch_execz .LBB0_238
	v_cmp_ge_i32_e32 vcc, s7, v181
	v_mov_b32_e32 v212, v198
	s_and_saveexec_b64 s[94:95], vcc
	s_cbranch_execz .LBB0_237
	ds_read2_b32 v[112:113], v211 offset0:64 offset1:65
	ds_read2_b32 v[114:115], v211 offset0:66 offset1:67
	ds_read2_b32 v[116:117], v211 offset0:72 offset1:73
	ds_read2_b32 v[118:119], v211 offset0:74 offset1:75
	ds_read2_b32 v[120:121], v211 offset0:80 offset1:81
	ds_read2_b32 v[122:123], v211 offset0:82 offset1:83
	ds_read2_b32 v[124:125], v211 offset0:88 offset1:89
	ds_read2_b32 v[126:127], v211 offset0:90 offset1:91
	ds_read2_b32 v[140:141], v211 offset0:96 offset1:97
	ds_read2_b32 v[142:143], v211 offset0:98 offset1:99
	ds_read2_b32 v[218:219], v211 offset0:104 offset1:105
	ds_read2_b32 v[220:221], v211 offset0:106 offset1:107
	s_waitcnt lgkmcnt(0)
	v_pk_add_f32 v[96:97], v[96:97], v[112:113]
	v_pk_add_f32 v[108:109], v[108:109], v[124:125]
	v_pk_add_f32 v[106:107], v[106:107], v[122:123]
	v_pk_add_f32 v[104:105], v[104:105], v[120:121]
	ds_read2_b32 v[112:113], v211 offset0:112 offset1:113
	ds_read2_b32 v[120:121], v211 offset0:114 offset1:115
	ds_read2_b32 v[122:123], v211 offset0:120 offset1:121
	ds_read2_b32 v[124:125], v211 offset0:122 offset1:123
	v_pk_add_f32 v[110:111], v[110:111], v[126:127]
	v_pk_add_f32 v[102:103], v[102:103], v[118:119]
	v_pk_add_f32 v[100:101], v[100:101], v[116:117]
	v_pk_add_f32 v[98:99], v[98:99], v[114:115]
	v_pk_add_f32 v[80:81], v[80:81], v[140:141]
	s_waitcnt lgkmcnt(0)
	v_pk_add_f32 v[94:95], v[94:95], v[124:125]
	v_pk_add_f32 v[92:93], v[92:93], v[122:123]
	v_pk_add_f32 v[90:91], v[90:91], v[120:121]
	v_pk_add_f32 v[88:89], v[88:89], v[112:113]
	v_pk_add_f32 v[86:87], v[86:87], v[220:221]
	v_pk_add_f32 v[84:85], v[84:85], v[218:219]
	v_pk_add_f32 v[82:83], v[82:83], v[142:143]
	v_mov_b32_e32 v212, 0

; #define SBAR() __builtin_amdgcn_sched_barrier(0)
; #define PIN(x) asm volatile("" : "+v"(x))
; #define VRD_(S, I) do { vl[S] = vtr(vp + v_rd_off((I) & 3, (I) >> 2, 0)); vh[S] = vtr(vp + v_rd_off((I) & 3, (I) >> 2, 1)); } while (0)
; template <int DK, bool NOMAX> ...
;     ...
; #pragma unroll
;   for (int i = 0; i < 16; ++i) {
;     if (i + 2 < 16) VRD_((i + 2) % 3, i + 2);
;     if (i == 1) { if (dk) __builtin_amdgcn_global_load_lds((const unsigned*)gk0, lk, 16, 0, 0); }
;     if (i == 3) { if constexpr (DK == 128) { if (dk) __builtin_amdgcn_global_load_lds((const unsigned*)gk1, (lds_up)((lds_cp)lk + 8192), 16, 0, 0); } }
;     if (i == 5) { if (dv) __builtin_amdgcn_global_load_lds((const unsigned*)gv0, lv, 16, 0, 0); }
;     if (i == 7) { if (dv) __builtin_amdgcn_global_load_lds((const unsigned*)gv1, (lds_up)((lds_cp)lv + 8192), 16, 0, 0); }
;     if (i == 12 || i == 13) { const int cb_ = ((i - 12) * 16 + hi * 8) * 2;
;       if constexpr (DK == 128) { kf[i - 12][0] = *reinterpret_cast<const bf16x8*>(Kn + KSWZ128(r32, cb_)); kf[i - 12][1] = *reinterpret_cast<const bf16x8*>(Kn + KSWZ128(32 + r32, cb_)); }
;       else { kf[i - 12][0] = *reinterpret_cast<const bf16x8*>(Kn + KSWZ64(r32, cb_)); kf[i - 12][1] = *reinterpret_cast<const bf16x8*>(Kn + KSWZ64(32 + r32, cb_)); } }
;     SBAR();
;     o[i & 3] = __builtin_amdgcn_mfma_f32_32x32x16_bf16(pa[i >> 2], VFR_(i % 3), o[i & 3], 0, 0, 0);
;     if constexpr (NOMAX) { c0[i] = __builtin_amdgcn_exp2f(c0[i]); c1[i] = __builtin_amdgcn_exp2f(c1[i]); if (i > 0) { psa += c0[i - 1]; psb += c1[i - 1]; } PIN(c0); PIN(c1); PIN(psa); PIN(psb); }
.LBB0_238:
	s_or_b64 exec, exec, s[4:5]
	s_cmpk_gt_u32 s97, 0x7b
	s_cselect_b64 s[4:5], -1, 0
	ds_read_b64_tr_b16 v[112:113], v217 offset:1024
	ds_read_b64_tr_b16 v[114:115], v217 offset:3072
	s_waitcnt lgkmcnt(4)
	v_mfma_f32_32x32x16_bf16 v[16:31], v[128:131], v[136:139], v[16:31]
	v_exp_f32_e32 v96, v96
	v_exp_f32_e32 v80, v80
	ds_read_b64_tr_b16 v[116:117], v217 offset:1536
	ds_read_b64_tr_b16 v[118:119], v217 offset:3584
	s_and_b64 vcc, exec, s[4:5]
	s_cbranch_vccnz .LBB0_240
	v_lshl_add_u64 v[124:125], v[164:165], 0, s[34:35]
	s_add_i32 m0, s3, s59
	s_nop 0
	global_load_lds_dwordx4 v[124:125], off
; template <int DK, bool NOMAX> ...
;     ...
; #pragma unroll
;   for (int i = 0; i < 16; ++i) {
;     if (i + 2 < 16) VRD_((i + 2) % 3, i + 2);
;     if (i == 1) { if (dk) __builtin_amdgcn_global_load_lds((const unsigned*)gk0, lk, 16, 0, 0); }
;     if (i == 3) { if constexpr (DK == 128) { if (dk) __builtin_amdgcn_global_load_lds((const unsigned*)gk1, (lds_up)((lds_cp)lk + 8192), 16, 0, 0); } }
;     if (i == 5) { if (dv) __builtin_amdgcn_global_load_lds((const unsigned*)gv0, lv, 16, 0, 0); }
;     if (i == 7) { if (dv) __builtin_amdgcn_global_load_lds((const unsigned*)gv1, (lds_up)((lds_cp)lv + 8192), 16, 0, 0); }
;     if (i == 12 || i == 13) { const int cb_ = ((i - 12) * 16 + hi * 8) * 2;
;       if constexpr (DK == 128) { kf[i - 12][0] = *reinterpret_cast<const bf16x8*>(Kn + KSWZ128(r32, cb_)); kf[i - 12][1] = *reinterpret_cast<const bf16x8*>(Kn + KSWZ128(32 + r32, cb_)); }
;       else { kf[i - 12][0] = *reinterpret_cast<const bf16x8*>(Kn + KSWZ64(r32, cb_)); kf[i - 12][1] = *reinterpret_cast<const bf16x8*>(Kn + KSWZ64(32 + r32, cb_)); } }
;     SBAR();
;     o[i & 3] = __builtin_amdgcn_mfma_f32_32x32x16_bf16(pa[i >> 2], VFR_(i % 3), o[i & 3], 0, 0, 0);
;     if constexpr (NOMAX) { c0[i] = __builtin_amdgcn_exp2f(c0[i]); c1[i] = __builtin_amdgcn_exp2f(c1[i]); if (i > 0) { psa += c0[i - 1]; psb += c1[i - 1]; } PIN(c0); PIN(c1); PIN(psa); PIN(psb); }
;     else {
;     if (i == 0) { ma = max3f(c0[0], c0[1], c1[0]); mb = max3f(c0[2], c0[3], c1[1]); ma = max3f(ma, c1[2], c1[3]); }
;     if (i >= 1 && i <= 3) { const int r = 4 * i; ma = max3f(ma, c0[r], c0[r + 1]); mb = max3f(mb, c0[r + 2], c0[r + 3]); ma = max3f(ma, c1[r], c1[r + 1]); mb = max3f(mb, c1[r + 2], c1[r + 3]); }
;     if (i == 4) { float pmax = fmaxf(ma, mb);
;       { auto rr = __builtin_amdgcn_permlane32_swap(__float_as_uint(pmax), __float_as_uint(pmax), false, false);
;         pmax = fmaxf(__uint_as_float(rr[0]), __uint_as_float(rr[1])); }
;       pmax += cb;
;       const bool keep = __all(pmax - m_reg <= THR2);
;       const float mn = keep ? m_reg : fmaxf(m_reg, pmax);
;       alpha = __builtin_amdgcn_exp2f(m_reg - mn); m_reg = mn; mnC = cb - mn; }
;     if (i >= 5 && i <= 8) { const int r = 4 * (i - 5);
; #pragma unroll
;       for (int q = 0; q < 4; ++q) { c0[r + q] += mnC; c1[r + q] += mnC; } }
;     if (i >= 9) { const int r0 = (i - 9) * 2 + (i > 14 ? 1 : 0), n = i >= 14 ? 3 : 2;
.LBB0_240:
	v_sub_f32_e32 v120, v215, v212
	v_exp_f32_e32 v120, v120
	s_add_i32 s59, s63, 0xffffc000
	s_and_b32 s59, s59, 0xc000
	s_add_i32 s59, s59, 0
	v_lshl_add_u64 v[126:127], v[166:167], 0, s[36:37]
	v_lshl_add_u64 v[136:137], v[168:169], 0, s[36:37]
	s_waitcnt lgkmcnt(4)
	v_mfma_f32_32x32x16_bf16 v[32:47], v[128:131], v[132:135], v[32:47]
	v_exp_f32_e32 v97, v97
	v_exp_f32_e32 v81, v81
	ds_read_b64_tr_b16 v[122:123], v217 offset:4096
	ds_read_b64_tr_b16 v[124:125], v217 offset:6144
	s_waitcnt lgkmcnt(4)
	v_mfma_f32_32x32x16_bf16 v[48:63], v[128:131], v[112:115], v[48:63]
	v_exp_f32_e32 v98, v98
	v_exp_f32_e32 v82, v82
	v_add_f32_e32 v132, v81, v80
	v_add_f32_e32 v121, v97, v96
	ds_read_b64_tr_b16 v[112:113], v217 offset:4608
	ds_read_b64_tr_b16 v[114:115], v217 offset:6656
	s_waitcnt lgkmcnt(4)
	v_mfma_f32_32x32x16_bf16 v[64:79], v[128:131], v[116:119], v[64:79]
	v_exp_f32_e32 v99, v99
	v_exp_f32_e32 v83, v83
	v_add_f32_e32 v128, v82, v132
	v_add_f32_e32 v121, v98, v121
	ds_read_b64_tr_b16 v[116:117], v217 offset:5120
	ds_read_b64_tr_b16 v[118:119], v217 offset:7168
	s_waitcnt lgkmcnt(4)
	v_mfma_f32_32x32x16_bf16 v[16:31], v[10:13], v[122:125], v[16:31]
	v_exp_f32_e32 v100, v100
	v_exp_f32_e32 v84, v84
	v_add_f32_e32 v128, v83, v128
	v_add_f32_e32 v121, v99, v121
	s_add_i32 s94, s62, s96
	s_mov_b32 m0, s94
	ds_read_b64_tr_b16 v[122:123], v217 offset:5632
	ds_read_b64_tr_b16 v[124:125], v217 offset:7680
	global_load_lds_dwordx4 v[126:127], off
	s_waitcnt lgkmcnt(4)
	v_mfma_f32_32x32x16_bf16 v[32:47], v[10:13], v[112:115], v[32:47]
	v_exp_f32_e32 v101, v101
	v_exp_f32_e32 v85, v85
	v_add_f32_e32 v126, v84, v128
	v_add_f32_e32 v121, v100, v121
	ds_read_b64_tr_b16 v[112:113], v217 offset:8192
	ds_read_b64_tr_b16 v[114:115], v217 offset:10240
	s_waitcnt lgkmcnt(4)
	v_mfma_f32_32x32x16_bf16 v[48:63], v[10:13], v[116:119], v[48:63]
	v_exp_f32_e32 v102, v102
	v_exp_f32_e32 v86, v86
	v_add_f32_e32 v126, v85, v126
	v_add_f32_e32 v121, v101, v121
	s_add_i32 m0, s94, 0x2000
	ds_read_b64_tr_b16 v[116:117], v217 offset:8704
	ds_read_b64_tr_b16 v[118:119], v217 offset:10752
	global_load_lds_dwordx4 v[136:137], off
	s_waitcnt lgkmcnt(4)
	v_mfma_f32_32x32x16_bf16 v[64:79], v[10:13], v[122:125], v[64:79]
	v_exp_f32_e32 v103, v103
	v_exp_f32_e32 v87, v87
	v_add_f32_e32 v122, v86, v126
	v_add_f32_e32 v121, v102, v121
	ds_read_b64_tr_b16 v[10:11], v217 offset:9216
	ds_read_b64_tr_b16 v[12:13], v217 offset:11264
	s_waitcnt lgkmcnt(4)
	v_mfma_f32_32x32x16_bf16 v[16:31], v[6:9], v[112:115], v[16:31]
	v_exp_f32_e32 v104, v104
	v_exp_f32_e32 v88, v88
	v_add_f32_e32 v122, v87, v122
	v_add_f32_e32 v121, v103, v121
	ds_read_b64_tr_b16 v[112:113], v217 offset:9728
	ds_read_b64_tr_b16 v[114:115], v217 offset:11776
	s_waitcnt lgkmcnt(4)
	v_mfma_f32_32x32x16_bf16 v[32:47], v[6:9], v[116:119], v[32:47]
	v_exp_f32_e32 v105, v105
	v_exp_f32_e32 v89, v89
	v_add_f32_e32 v116, v88, v122
	v_add_f32_e32 v117, v104, v121
	ds_read_b64_tr_b16 v[122:123], v217 offset:12288
	ds_read_b64_tr_b16 v[124:125], v217 offset:14336
	s_waitcnt lgkmcnt(4)
	v_mfma_f32_32x32x16_bf16 v[48:63], v[6:9], v[10:13], v[48:63]
	v_exp_f32_e32 v106, v106
	v_exp_f32_e32 v90, v90
	v_add_f32_e32 v10, v89, v116
	v_add_f32_e32 v11, v105, v117
	ds_read_b64_tr_b16 v[126:127], v217 offset:12800
	ds_read_b64_tr_b16 v[128:129], v217 offset:14848
	s_waitcnt lgkmcnt(4)
	v_mfma_f32_32x32x16_bf16 v[64:79], v[6:9], v[112:115], v[64:79]
	v_exp_f32_e32 v107, v107
	v_exp_f32_e32 v91, v91
	v_add_f32_e32 v6, v90, v10
	v_add_f32_e32 v7, v106, v11
	v_add_u32_e32 v8, s59, v209
	ds_read_b64_tr_b16 v[130:131], v217 offset:13312
	ds_read_b64_tr_b16 v[132:133], v217 offset:15360
	ds_read_b128 v[116:119], v8
	ds_read_b128 v[112:115], v8 offset:4096
	s_waitcnt lgkmcnt(6)
	v_mfma_f32_32x32x16_bf16 v[16:31], v[2:5], v[122:125], v[16:31]
	v_exp_f32_e32 v108, v108
	v_exp_f32_e32 v92, v92
	v_add_f32_e32 v121, v91, v6
	v_add_f32_e32 v134, v107, v7
	v_add_u32_e32 v6, s59, v210
	ds_read_b64_tr_b16 v[122:123], v217 offset:13824
	ds_read_b64_tr_b16 v[124:125], v217 offset:15872
	ds_read_b128 v[10:13], v6
	ds_read_b128 v[6:9], v6 offset:4096
	s_waitcnt lgkmcnt(8)
	v_mfma_f32_32x32x16_bf16 v[32:47], v[2:5], v[126:129], v[32:47]
	v_exp_f32_e32 v109, v109
	v_exp_f32_e32 v93, v93
	v_add_f32_e32 v121, v92, v121
	v_add_f32_e32 v126, v108, v134
	s_waitcnt lgkmcnt(6)
	v_mfma_f32_32x32x16_bf16 v[48:63], v[2:5], v[130:133], v[48:63]
	v_exp_f32_e32 v110, v110
	v_exp_f32_e32 v94, v94
	v_add_f32_e32 v121, v93, v121
	v_add_f32_e32 v126, v109, v126
	s_waitcnt lgkmcnt(2)
	v_mfma_f32_32x32x16_bf16 v[64:79], v[2:5], v[122:125], v[64:79]
	v_exp_f32_e32 v111, v111
	v_exp_f32_e32 v95, v95
	v_add_f32_e32 v2, v94, v121
	v_add_f32_e32 v3, v110, v126
	s_nop 0
	v_add_f32_e32 v3, v111, v3
	v_add_f32_e32 v2, v95, v2
	v_add_f32_e32 v2, v3, v2
	v_mov_b32_e32 v3, v2
	s_nop 1
	v_permlane32_swap_b32_e32 v2, v3
	v_cmp_neq_f32_e32 vcc, 1.0, v120
	s_cbranch_vccz .LBB0_244
	s_and_saveexec_b64 s[94:95], s[46:47]
	ds_write_b32 v188, v120 offset:128
	s_or_b64 exec, exec, s[94:95]
	s_waitcnt lgkmcnt(0)
	v_add_u32_e32 v4, s2, v171
	ds_read_b128 v[122:125], v4 offset:224
	ds_read_b128 v[126:129], v4 offset:192
	ds_read_b128 v[130:133], v4 offset:160
	ds_read_b128 v[134:137], v4 offset:128
	s_waitcnt lgkmcnt(0)
	v_pk_mul_f32 v[28:29], v[28:29], v[122:123]
	v_pk_mul_f32 v[24:25], v[24:25], v[126:127]
	v_pk_mul_f32 v[20:21], v[20:21], v[130:131]
	v_pk_mul_f32 v[30:31], v[30:31], v[124:125]
	v_pk_mul_f32 v[26:27], v[26:27], v[128:129]
	v_pk_mul_f32 v[22:23], v[22:23], v[132:133]
	v_pk_mul_f32 v[18:19], v[18:19], v[136:137]
	v_pk_mul_f32 v[16:17], v[16:17], v[134:135]
	v_pk_mul_f32 v[44:45], v[44:45], v[122:123]
	v_pk_mul_f32 v[40:41], v[40:41], v[126:127]
	v_pk_mul_f32 v[36:37], v[36:37], v[130:131]
	v_pk_mul_f32 v[46:47], v[46:47], v[124:125]
	v_pk_mul_f32 v[42:43], v[42:43], v[128:129]
	v_pk_mul_f32 v[38:39], v[38:39], v[132:133]
	v_pk_mul_f32 v[34:35], v[34:35], v[136:137]
	v_pk_mul_f32 v[32:33], v[32:33], v[134:135]
	v_pk_mul_f32 v[60:61], v[60:61], v[122:123]
	v_pk_mul_f32 v[56:57], v[56:57], v[126:127]
	v_pk_mul_f32 v[52:53], v[52:53], v[130:131]
	v_pk_mul_f32 v[62:63], v[62:63], v[124:125]
	v_pk_mul_f32 v[58:59], v[58:59], v[128:129]
	v_pk_mul_f32 v[54:55], v[54:55], v[132:133]
	v_pk_mul_f32 v[50:51], v[50:51], v[136:137]
	v_pk_mul_f32 v[48:49], v[48:49], v[134:135]
	v_pk_mul_f32 v[76:77], v[76:77], v[122:123]
	v_pk_mul_f32 v[72:73], v[72:73], v[126:127]
	v_pk_mul_f32 v[68:69], v[68:69], v[130:131]
	v_pk_mul_f32 v[78:79], v[78:79], v[124:125]
	v_pk_mul_f32 v[74:75], v[74:75], v[128:129]
	v_pk_mul_f32 v[70:71], v[70:71], v[132:133]
	v_pk_mul_f32 v[66:67], v[66:67], v[136:137]
	v_pk_mul_f32 v[64:65], v[64:65], v[134:135]

; #define SBAR() __builtin_amdgcn_sched_barrier(0)
; __device__ __forceinline__ s16x4 vtr(lds_cptr p) { return __builtin_bit_cast(s16x4, __builtin_amdgcn_ds_read_tr16_b64_v4i16((__attribute__((address_space(3))) v4i16_t*)p)); }
; #define PIN(x) asm volatile("" : "+v"(x))
; __device__ __forceinline__ void add_bias(f32x16& p0, f32x16& p1, const float* tb, int relb, int hi) {
;   const float* t = tb + relb + 4 * hi;
; #pragma unroll
;   for (int r = 0; r < 16; ++r) { p0[r] += t[(r & 3) + 8 * (r >> 2)]; p1[r] += t[32 + (r & 3) + 8 * (r >> 2)]; }
; template <int DK, bool NOMAX> ...
;     ...
;   float psa = 0.f, psb = 0.f;
;   SBAR();
; #pragma unroll
;   for (int d0 = 0; d0 < NS; ++d0) {
;     if (d0 == 0) { c0 = __builtin_amdgcn_mfma_f32_32x32x16_bf16(kf[0][0], qr[0], f32x16{}, 0, 0, 0); c1 = __builtin_amdgcn_mfma_f32_32x32x16_bf16(kf[0][1], qr[0], f32x16{}, 0, 0, 0); }
;     else { c0 = __builtin_amdgcn_mfma_f32_32x32x16_bf16(kf[d0 & 1][0], qr[d0], c0, 0, 0, 0); c1 = __builtin_amdgcn_mfma_f32_32x32x16_bf16(kf[d0 & 1][1], qr[d0], c1, 0, 0, 0); }
;     if (d0 + 2 < NS) KRD_(d0 & 1, d0 + 2);
;     if constexpr (NOMAX) { }
;     else {
; #pragma unroll
;     for (int r = d0 * RPS; r < (d0 + 1) * RPS; ++r) { p1[r] = __builtin_amdgcn_exp2f(p1[r]); psa += p0[r]; }
;     if (d0 > 0) {
; #pragma unroll
;       for (int r = (d0 - 1) * RPS; r < d0 * RPS; ++r) psb += p1[r]; } }
;     if constexpr (NOMAX) {
;       if (d0 == NS / 4 - 1) { PK4R(p0, 0, pa[0]); PIN(pa[0]); }
;       if (d0 == NS / 2 - 1) { PK4R(p0, 8, pa[1]); PIN(pa[1]); }
;       if (d0 == 3 * NS / 4 - 1) { PK4R(p1, 0, pa[2]); PIN(pa[2]); }
;       if (d0 == NS - 1) { PK4R(p1, 8, pa[3]); PIN(pa[3]); }
;     } else {
;     if (d0 == NS / 2 - 1) { PK4R(p0, 0, pa[0]); PIN(pa[0]); }
;     if (d0 == NS / 2) { PK4R(p0, 8, pa[1]); PIN(pa[1]); }
;     if (d0 == NS - 1) { PK4R(p1, 0, pa[2]); PIN(pa[2]); }
;     }
;     if (d0 == NS - 1) {
;       vl[0] = vtr(vp + v_rd_off(0, 0, 0)); vh[0] = vtr(vp + v_rd_off(0, 0, 1)); vl[1] = vtr(vp + v_rd_off(1, 0, 0)); vh[1] = vtr(vp + v_rd_off(1, 0, 1)); }
;     PIN(p1); PIN(psa); PIN(psb);
;     SBAR();
;   }
.LBB0_313:
	s_mov_b32 s58, s95
	s_mov_b32 s95, s4
	s_add_i32 s4, s63, 0xffff4000
	s_and_b32 s59, s4, 0xc000
	s_add_i32 s4, s59, 0
	v_add_u32_e32 v213, s95, v187
	s_waitcnt lgkmcnt(0)
	v_mfma_f32_32x32x16_bf16 v[128:143], v[116:119], v[156:159], 0
	v_add_u32_e32 v0, s4, v207
	ds_read_b128 v[2:5], v0
	ds_read_b128 v[164:167], v0 offset:4096
	v_cvt_pk_bf16_f32 v96, v96, v97
	v_cvt_pk_bf16_f32 v97, v98, v99
	v_cvt_pk_bf16_f32 v98, v100, v101
	v_cvt_pk_bf16_f32 v99, v102, v103
	v_mfma_f32_32x32x16_bf16 v[112:127], v[112:115], v[156:159], 0
	v_permlane32_swap_b32_e32 v96, v98
	v_permlane32_swap_b32_e32 v97, v99
	v_mfma_f32_32x32x16_bf16 v[128:143], v[10:13], v[152:155], v[128:143]
	v_mfma_f32_32x32x16_bf16 v[112:127], v[6:9], v[152:155], v[112:127]
	v_add_u32_e32 v6, s4, v208
	ds_read_b128 v[100:103], v6
	ds_read_b128 v[214:217], v6 offset:4096
	v_cvt_pk_bf16_f32 v10, v104, v105
	v_cvt_pk_bf16_f32 v11, v106, v107
	v_cvt_pk_bf16_f32 v12, v108, v109
	v_cvt_pk_bf16_f32 v13, v110, v111
	s_nop 0
	v_permlane32_swap_b32_e32 v10, v12
	v_permlane32_swap_b32_e32 v11, v13
	s_waitcnt lgkmcnt(3)
	v_mfma_f32_32x32x16_bf16 v[128:143], v[2:5], v[148:151], v[128:143]
	v_cvt_pk_bf16_f32 v6, v80, v81
	v_cvt_pk_bf16_f32 v7, v82, v83
	v_cvt_pk_bf16_f32 v8, v84, v85
	v_cvt_pk_bf16_f32 v9, v86, v87
	s_nop 0
	v_permlane32_swap_b32_e32 v6, v8
	s_waitcnt lgkmcnt(2)
	v_mfma_f32_32x32x16_bf16 v[112:127], v[164:167], v[148:151], v[112:127]
	v_permlane32_swap_b32_e32 v7, v9
	s_nop 0
	v_cvt_pk_bf16_f32 v2, v88, v89
	v_cvt_pk_bf16_f32 v3, v90, v91
	v_cvt_pk_bf16_f32 v4, v92, v93
	v_cvt_pk_bf16_f32 v5, v94, v95
	s_waitcnt lgkmcnt(1)
	v_mfma_f32_32x32x16_bf16 v[128:143], v[100:103], v[144:147], v[128:143]
	v_permlane32_swap_b32_e32 v2, v4
	v_permlane32_swap_b32_e32 v3, v5
	ds_read_b64_tr_b16 v[104:105], v213
	ds_read_b64_tr_b16 v[106:107], v213 offset:2048
	ds_read_b64_tr_b16 v[100:101], v213 offset:512
	ds_read_b64_tr_b16 v[102:103], v213 offset:2560
	s_waitcnt lgkmcnt(4)
	v_mfma_f32_32x32x16_bf16 v[112:127], v[214:217], v[144:147], v[112:127]
	v_add_u32_e32 v216, s94, v205
	v_add_u32_e32 v0, 0xffffffa1, v216
	v_cmp_gt_i32_e32 vcc, s67, v0
	v_mov_b32_e32 v215, v199
	s_and_saveexec_b64 s[4:5], vcc
	s_cbranch_execz .LBB0_317
	v_subrev_u32_e32 v0, 64, v216
	v_cmp_lt_i32_e32 vcc, s77, v0
	v_mov_b32_e32 v215, v198
	s_and_saveexec_b64 s[16:17], vcc
	s_cbranch_execz .LBB0_316
	ds_read2_b32 v[80:81], v211 offset1:1
	ds_read2_b32 v[82:83], v211 offset0:2 offset1:3
	ds_read2_b32 v[84:85], v211 offset0:8 offset1:9
	ds_read2_b32 v[86:87], v211 offset0:10 offset1:11
	ds_read2_b32 v[88:89], v211 offset0:16 offset1:17
	ds_read2_b32 v[90:91], v211 offset0:18 offset1:19
	ds_read2_b32 v[92:93], v211 offset0:24 offset1:25
	ds_read2_b32 v[94:95], v211 offset0:26 offset1:27
	ds_read2_b32 v[108:109], v211 offset0:32 offset1:33
	ds_read2_b32 v[110:111], v211 offset0:34 offset1:35
	ds_read2_b32 v[164:165], v211 offset0:40 offset1:41
	ds_read2_b32 v[166:167], v211 offset0:42 offset1:43
	s_waitcnt lgkmcnt(0)
	v_pk_add_f32 v[128:129], v[128:129], v[80:81]
	v_pk_add_f32 v[140:141], v[140:141], v[92:93]
	v_pk_add_f32 v[138:139], v[138:139], v[90:91]
	v_pk_add_f32 v[136:137], v[136:137], v[88:89]
	ds_read2_b32 v[80:81], v211 offset0:48 offset1:49
	ds_read2_b32 v[88:89], v211 offset0:50 offset1:51
	ds_read2_b32 v[90:91], v211 offset0:56 offset1:57
	ds_read2_b32 v[92:93], v211 offset0:58 offset1:59
	v_pk_add_f32 v[142:143], v[142:143], v[94:95]
	v_pk_add_f32 v[134:135], v[134:135], v[86:87]
	v_pk_add_f32 v[132:133], v[132:133], v[84:85]
	v_pk_add_f32 v[130:131], v[130:131], v[82:83]
	v_pk_add_f32 v[112:113], v[112:113], v[108:109]
	s_waitcnt lgkmcnt(0)
	v_pk_add_f32 v[126:127], v[126:127], v[92:93]
	v_pk_add_f32 v[124:125], v[124:125], v[90:91]
	v_pk_add_f32 v[122:123], v[122:123], v[88:89]
	v_pk_add_f32 v[120:121], v[120:121], v[80:81]
	v_pk_add_f32 v[118:119], v[118:119], v[166:167]
	v_pk_add_f32 v[116:117], v[116:117], v[164:165]
	v_pk_add_f32 v[114:115], v[114:115], v[110:111]
	v_mov_b32_e32 v215, 0

; #define SBAR() __builtin_amdgcn_sched_barrier(0)
; #define PIN(x) asm volatile("" : "+v"(x))
; #define VRD_(S, I) do { vl[S] = vtr(vp + v_rd_off((I) & 3, (I) >> 2, 0)); vh[S] = vtr(vp + v_rd_off((I) & 3, (I) >> 2, 1)); } while (0)
; template <int DK, bool NOMAX> ...
;     ...
; #pragma unroll
;   for (int i = 0; i < 16; ++i) {
;     if (i + 2 < 16) VRD_((i + 2) % 3, i + 2);
;     if (i == 1) { if (dk) __builtin_amdgcn_global_load_lds((const unsigned*)gk0, lk, 16, 0, 0); }
;     if (i == 3) { if constexpr (DK == 128) { if (dk) __builtin_amdgcn_global_load_lds((const unsigned*)gk1, (lds_up)((lds_cp)lk + 8192), 16, 0, 0); } }
;     if (i == 5) { if (dv) __builtin_amdgcn_global_load_lds((const unsigned*)gv0, lv, 16, 0, 0); }
;     if (i == 7) { if (dv) __builtin_amdgcn_global_load_lds((const unsigned*)gv1, (lds_up)((lds_cp)lv + 8192), 16, 0, 0); }
;     if (i == 12 || i == 13) { const int cb_ = ((i - 12) * 16 + hi * 8) * 2;
;       if constexpr (DK == 128) { kf[i - 12][0] = *reinterpret_cast<const bf16x8*>(Kn + KSWZ128(r32, cb_)); kf[i - 12][1] = *reinterpret_cast<const bf16x8*>(Kn + KSWZ128(32 + r32, cb_)); }
;       else { kf[i - 12][0] = *reinterpret_cast<const bf16x8*>(Kn + KSWZ64(r32, cb_)); kf[i - 12][1] = *reinterpret_cast<const bf16x8*>(Kn + KSWZ64(32 + r32, cb_)); } }
;     SBAR();
;     o[i & 3] = __builtin_amdgcn_mfma_f32_32x32x16_bf16(pa[i >> 2], VFR_(i % 3), o[i & 3], 0, 0, 0);
;     if constexpr (NOMAX) { c0[i] = __builtin_amdgcn_exp2f(c0[i]); c1[i] = __builtin_amdgcn_exp2f(c1[i]); if (i > 0) { psa += c0[i - 1]; psb += c1[i - 1]; } PIN(c0); PIN(c1); PIN(psa); PIN(psb); }
.LBB0_317:
	s_or_b64 exec, exec, s[4:5]
	s_add_i32 s96, s96, 2
	s_cmp_gt_u32 s96, 60
	s_cselect_b64 s[16:17], -1, 0
	ds_read_b64_tr_b16 v[80:81], v213 offset:1024
	ds_read_b64_tr_b16 v[82:83], v213 offset:3072
	s_waitcnt lgkmcnt(4)
	v_mfma_f32_32x32x16_bf16 v[16:31], v[96:99], v[104:107], v[16:31]
	v_exp_f32_e32 v128, v128
	v_exp_f32_e32 v112, v112
	ds_read_b64_tr_b16 v[84:85], v213 offset:1536
	ds_read_b64_tr_b16 v[86:87], v213 offset:3584
	s_and_b64 vcc, exec, s[16:17]
	v_lshl_add_u64 v[164:165], s[0:1], 0, v[162:163]
	s_cbranch_vccnz .LBB0_319
	s_and_b32 s4, s63, 0xc000
	v_lshl_add_u64 v[90:91], v[164:165], 0, s[28:29]
	s_add_i32 m0, s3, s4
	s_nop 0
	global_load_lds_dwordx4 v[90:91], off
; template <int DK, bool NOMAX> ...
;     ...
; #pragma unroll
;   for (int i = 0; i < 16; ++i) {
;     if (i + 2 < 16) VRD_((i + 2) % 3, i + 2);
;     if (i == 1) { if (dk) __builtin_amdgcn_global_load_lds((const unsigned*)gk0, lk, 16, 0, 0); }
;     if (i == 3) { if constexpr (DK == 128) { if (dk) __builtin_amdgcn_global_load_lds((const unsigned*)gk1, (lds_up)((lds_cp)lk + 8192), 16, 0, 0); } }
;     if (i == 5) { if (dv) __builtin_amdgcn_global_load_lds((const unsigned*)gv0, lv, 16, 0, 0); }
;     if (i == 7) { if (dv) __builtin_amdgcn_global_load_lds((const unsigned*)gv1, (lds_up)((lds_cp)lv + 8192), 16, 0, 0); }
;     if (i == 12 || i == 13) { const int cb_ = ((i - 12) * 16 + hi * 8) * 2;
;       if constexpr (DK == 128) { kf[i - 12][0] = *reinterpret_cast<const bf16x8*>(Kn + KSWZ128(r32, cb_)); kf[i - 12][1] = *reinterpret_cast<const bf16x8*>(Kn + KSWZ128(32 + r32, cb_)); }
;       else { kf[i - 12][0] = *reinterpret_cast<const bf16x8*>(Kn + KSWZ64(r32, cb_)); kf[i - 12][1] = *reinterpret_cast<const bf16x8*>(Kn + KSWZ64(32 + r32, cb_)); } }
;     SBAR();
;     o[i & 3] = __builtin_amdgcn_mfma_f32_32x32x16_bf16(pa[i >> 2], VFR_(i % 3), o[i & 3], 0, 0, 0);
;     if constexpr (NOMAX) { c0[i] = __builtin_amdgcn_exp2f(c0[i]); c1[i] = __builtin_amdgcn_exp2f(c1[i]); if (i > 0) { psa += c0[i - 1]; psb += c1[i - 1]; } PIN(c0); PIN(c1); PIN(psa); PIN(psb); }
;     else {
;     if (i == 0) { ma = max3f(c0[0], c0[1], c1[0]); mb = max3f(c0[2], c0[3], c1[1]); ma = max3f(ma, c1[2], c1[3]); }
;     if (i >= 1 && i <= 3) { const int r = 4 * i; ma = max3f(ma, c0[r], c0[r + 1]); mb = max3f(mb, c0[r + 2], c0[r + 3]); ma = max3f(ma, c1[r], c1[r + 1]); mb = max3f(mb, c1[r + 2], c1[r + 3]); }
;     if (i == 4) { float pmax = fmaxf(ma, mb);
;       { auto rr = __builtin_amdgcn_permlane32_swap(__float_as_uint(pmax), __float_as_uint(pmax), false, false);
;         pmax = fmaxf(__uint_as_float(rr[0]), __uint_as_float(rr[1])); }
;       pmax += cb;
;       const bool keep = __all(pmax - m_reg <= THR2);
;       const float mn = keep ? m_reg : fmaxf(m_reg, pmax);
;       alpha = __builtin_amdgcn_exp2f(m_reg - mn); m_reg = mn; mnC = cb - mn; }
;     if (i >= 5 && i <= 8) { const int r = 4 * (i - 5);
; #pragma unroll
;       for (int q = 0; q < 4; ++q) { c0[r + q] += mnC; c1[r + q] += mnC; } }
;     if (i >= 9) { const int r0 = (i - 9) * 2 + (i > 14 ? 1 : 0), n = i >= 14 ? 3 : 2;
.LBB0_319:
	v_sub_f32_e32 v0, v212, v215
	v_exp_f32_e32 v0, v0
	s_add_i32 s4, s63, 0xffff8000
	s_and_b32 s4, s4, 0xc000
	s_add_i32 s18, s4, 0
	v_lshl_add_u64 v[166:167], s[0:1], 0, v[160:161]
	v_lshl_add_u64 v[168:169], s[0:1], 0, v[14:15]
	v_lshl_add_u64 v[92:93], v[166:167], 0, s[30:31]
	v_lshl_add_u64 v[94:95], v[168:169], 0, s[30:31]
	s_waitcnt lgkmcnt(4)
	v_mfma_f32_32x32x16_bf16 v[32:47], v[96:99], v[100:103], v[32:47]
	v_exp_f32_e32 v129, v129
	v_exp_f32_e32 v113, v113
	ds_read_b64_tr_b16 v[88:89], v213 offset:4096
	ds_read_b64_tr_b16 v[90:91], v213 offset:6144
	s_waitcnt lgkmcnt(4)
	v_mfma_f32_32x32x16_bf16 v[48:63], v[96:99], v[80:83], v[48:63]
	v_exp_f32_e32 v130, v130
	v_exp_f32_e32 v114, v114
	v_add_f32_e32 v100, v113, v112
	v_add_f32_e32 v101, v129, v128
	ds_read_b64_tr_b16 v[80:81], v213 offset:4608
	ds_read_b64_tr_b16 v[82:83], v213 offset:6656
	s_waitcnt lgkmcnt(4)
	v_mfma_f32_32x32x16_bf16 v[64:79], v[96:99], v[84:87], v[64:79]
	v_exp_f32_e32 v131, v131
	v_exp_f32_e32 v115, v115
	v_add_f32_e32 v96, v114, v100
	v_add_f32_e32 v97, v130, v101
	ds_read_b64_tr_b16 v[84:85], v213 offset:5120
	ds_read_b64_tr_b16 v[86:87], v213 offset:7168
	s_waitcnt lgkmcnt(4)
	v_mfma_f32_32x32x16_bf16 v[16:31], v[10:13], v[88:91], v[16:31]
	v_exp_f32_e32 v132, v132
	v_exp_f32_e32 v116, v116
	v_add_f32_e32 v96, v115, v96
	v_add_f32_e32 v97, v131, v97
	s_add_i32 s4, s62, s97
	s_mov_b32 m0, s4
	ds_read_b64_tr_b16 v[88:89], v213 offset:5632
	ds_read_b64_tr_b16 v[90:91], v213 offset:7680
	global_load_lds_dwordx4 v[92:93], off
	s_waitcnt lgkmcnt(4)
	v_mfma_f32_32x32x16_bf16 v[32:47], v[10:13], v[80:83], v[32:47]
	v_exp_f32_e32 v133, v133
	v_exp_f32_e32 v117, v117
	v_add_f32_e32 v92, v116, v96
	v_add_f32_e32 v93, v132, v97
	ds_read_b64_tr_b16 v[80:81], v213 offset:8192
	ds_read_b64_tr_b16 v[82:83], v213 offset:10240
	s_waitcnt lgkmcnt(4)
	v_mfma_f32_32x32x16_bf16 v[48:63], v[10:13], v[84:87], v[48:63]
	v_exp_f32_e32 v134, v134
	v_exp_f32_e32 v118, v118
	v_add_f32_e32 v92, v117, v92
	v_add_f32_e32 v93, v133, v93
	s_add_i32 m0, s4, 0x2000
	ds_read_b64_tr_b16 v[84:85], v213 offset:8704
	ds_read_b64_tr_b16 v[86:87], v213 offset:10752
	global_load_lds_dwordx4 v[94:95], off
	s_waitcnt lgkmcnt(4)
	v_mfma_f32_32x32x16_bf16 v[64:79], v[10:13], v[88:91], v[64:79]
	v_exp_f32_e32 v135, v135
	v_exp_f32_e32 v119, v119
	v_add_f32_e32 v88, v118, v92
	v_add_f32_e32 v89, v134, v93
	ds_read_b64_tr_b16 v[10:11], v213 offset:9216
	ds_read_b64_tr_b16 v[12:13], v213 offset:11264
	s_waitcnt lgkmcnt(4)
	v_mfma_f32_32x32x16_bf16 v[16:31], v[6:9], v[80:83], v[16:31]
	v_exp_f32_e32 v136, v136
	v_exp_f32_e32 v120, v120
	v_add_f32_e32 v88, v119, v88
	v_add_f32_e32 v89, v135, v89
	ds_read_b64_tr_b16 v[80:81], v213 offset:9728
	ds_read_b64_tr_b16 v[82:83], v213 offset:11776
	s_waitcnt lgkmcnt(4)
	v_mfma_f32_32x32x16_bf16 v[32:47], v[6:9], v[84:87], v[32:47]
	v_exp_f32_e32 v137, v137
	v_exp_f32_e32 v121, v121
	v_add_f32_e32 v84, v120, v88
	v_add_f32_e32 v85, v136, v89
	ds_read_b64_tr_b16 v[88:89], v213 offset:12288
	ds_read_b64_tr_b16 v[90:91], v213 offset:14336
	s_waitcnt lgkmcnt(4)
	v_mfma_f32_32x32x16_bf16 v[48:63], v[6:9], v[10:13], v[48:63]
	v_exp_f32_e32 v138, v138
	v_exp_f32_e32 v122, v122
	v_add_f32_e32 v10, v121, v84
	v_add_f32_e32 v11, v137, v85
	ds_read_b64_tr_b16 v[92:93], v213 offset:12800
	ds_read_b64_tr_b16 v[94:95], v213 offset:14848
	s_waitcnt lgkmcnt(4)
	v_mfma_f32_32x32x16_bf16 v[64:79], v[6:9], v[80:83], v[64:79]
	v_exp_f32_e32 v139, v139
	v_exp_f32_e32 v123, v123
	v_add_f32_e32 v6, v122, v10
	v_add_f32_e32 v7, v138, v11
	v_add_u32_e32 v8, s18, v209
	ds_read_b64_tr_b16 v[96:97], v213 offset:13312
	ds_read_b64_tr_b16 v[98:99], v213 offset:15360
	ds_read_b128 v[80:83], v8
	ds_read_b128 v[84:87], v8 offset:4096
	s_waitcnt lgkmcnt(6)
	v_mfma_f32_32x32x16_bf16 v[16:31], v[2:5], v[88:91], v[16:31]
	v_exp_f32_e32 v140, v140
	v_exp_f32_e32 v124, v124
	v_add_f32_e32 v100, v123, v6
	v_add_f32_e32 v101, v139, v7
	v_add_u32_e32 v10, s18, v210
	ds_read_b64_tr_b16 v[88:89], v213 offset:13824
	ds_read_b64_tr_b16 v[90:91], v213 offset:15872
	ds_read_b128 v[6:9], v10
	ds_read_b128 v[10:13], v10 offset:4096
	s_waitcnt lgkmcnt(8)
	v_mfma_f32_32x32x16_bf16 v[32:47], v[2:5], v[92:95], v[32:47]
	v_exp_f32_e32 v141, v141
	v_exp_f32_e32 v125, v125
	v_add_f32_e32 v92, v124, v100
	v_add_f32_e32 v93, v140, v101
	s_waitcnt lgkmcnt(6)
	v_mfma_f32_32x32x16_bf16 v[48:63], v[2:5], v[96:99], v[48:63]
	v_exp_f32_e32 v142, v142
	v_exp_f32_e32 v126, v126
	v_add_f32_e32 v92, v125, v92
	v_add_f32_e32 v93, v141, v93
	s_waitcnt lgkmcnt(2)
	v_mfma_f32_32x32x16_bf16 v[64:79], v[2:5], v[88:91], v[64:79]
	v_exp_f32_e32 v143, v143
	v_exp_f32_e32 v127, v127
	v_add_f32_e32 v2, v126, v92
	v_add_f32_e32 v3, v142, v93
	s_nop 0
	v_add_f32_e32 v3, v143, v3
	v_add_f32_e32 v2, v127, v2
	v_add_f32_e32 v213, v3, v2
	v_mov_b32_e32 v214, v213
	s_nop 1
	v_permlane32_swap_b32_e32 v213, v214
	v_cmp_neq_f32_e32 vcc, 1.0, v0
	s_cbranch_vccz .LBB0_323
	s_and_saveexec_b64 s[4:5], s[46:47]
	ds_write_b32 v188, v0 offset:128
	s_or_b64 exec, exec, s[4:5]
	s_waitcnt lgkmcnt(0)
	v_add_u32_e32 v96, s2, v170
	ds_read_b128 v[2:5], v96 offset:224
	ds_read_b128 v[88:91], v96 offset:192
	ds_read_b128 v[92:95], v96 offset:160
	ds_read_b128 v[96:99], v96 offset:128
	s_waitcnt lgkmcnt(0)
	v_pk_mul_f32 v[28:29], v[28:29], v[2:3]
	v_pk_mul_f32 v[24:25], v[24:25], v[88:89]
	v_pk_mul_f32 v[20:21], v[20:21], v[92:93]
	v_pk_mul_f32 v[30:31], v[30:31], v[4:5]
	v_pk_mul_f32 v[26:27], v[26:27], v[90:91]
	v_pk_mul_f32 v[22:23], v[22:23], v[94:95]
	v_pk_mul_f32 v[18:19], v[18:19], v[98:99]
	v_pk_mul_f32 v[16:17], v[16:17], v[96:97]
	v_pk_mul_f32 v[44:45], v[44:45], v[2:3]
	v_pk_mul_f32 v[40:41], v[40:41], v[88:89]
	v_pk_mul_f32 v[36:37], v[36:37], v[92:93]
	v_pk_mul_f32 v[46:47], v[46:47], v[4:5]
	v_pk_mul_f32 v[42:43], v[42:43], v[90:91]
	v_pk_mul_f32 v[38:39], v[38:39], v[94:95]
	v_pk_mul_f32 v[34:35], v[34:35], v[98:99]
	v_pk_mul_f32 v[32:33], v[32:33], v[96:97]
	v_pk_mul_f32 v[60:61], v[60:61], v[2:3]
	v_pk_mul_f32 v[56:57], v[56:57], v[88:89]
	v_pk_mul_f32 v[52:53], v[52:53], v[92:93]
	v_pk_mul_f32 v[62:63], v[62:63], v[4:5]
	v_pk_mul_f32 v[58:59], v[58:59], v[90:91]
	v_pk_mul_f32 v[54:55], v[54:55], v[94:95]
	v_pk_mul_f32 v[50:51], v[50:51], v[98:99]
	v_pk_mul_f32 v[48:49], v[48:49], v[96:97]
	v_pk_mul_f32 v[76:77], v[76:77], v[2:3]
	v_pk_mul_f32 v[72:73], v[72:73], v[88:89]
	v_pk_mul_f32 v[68:69], v[68:69], v[92:93]
	v_pk_mul_f32 v[78:79], v[78:79], v[4:5]
	v_pk_mul_f32 v[74:75], v[74:75], v[90:91]
	v_pk_mul_f32 v[70:71], v[70:71], v[94:95]
	v_pk_mul_f32 v[66:67], v[66:67], v[98:99]
	v_pk_mul_f32 v[64:65], v[64:65], v[96:97]

; #define SBAR() __builtin_amdgcn_sched_barrier(0)
; __device__ __forceinline__ s16x4 vtr(lds_cptr p) { return __builtin_bit_cast(s16x4, __builtin_amdgcn_ds_read_tr16_b64_v4i16((__attribute__((address_space(3))) v4i16_t*)p)); }
; #define PIN(x) asm volatile("" : "+v"(x))
; __device__ __forceinline__ void add_bias(f32x16& p0, f32x16& p1, const float* tb, int relb, int hi) {
;   const float* t = tb + relb + 4 * hi;
; #pragma unroll
;   for (int r = 0; r < 16; ++r) { p0[r] += t[(r & 3) + 8 * (r >> 2)]; p1[r] += t[32 + (r & 3) + 8 * (r >> 2)]; }
; template <int DK, bool NOMAX> ...
;     ...
;   float psa = 0.f, psb = 0.f;
;   SBAR();
; #pragma unroll
;   for (int d0 = 0; d0 < NS; ++d0) {
;     if (d0 == 0) { c0 = __builtin_amdgcn_mfma_f32_32x32x16_bf16(kf[0][0], qr[0], f32x16{}, 0, 0, 0); c1 = __builtin_amdgcn_mfma_f32_32x32x16_bf16(kf[0][1], qr[0], f32x16{}, 0, 0, 0); }
;     else { c0 = __builtin_amdgcn_mfma_f32_32x32x16_bf16(kf[d0 & 1][0], qr[d0], c0, 0, 0, 0); c1 = __builtin_amdgcn_mfma_f32_32x32x16_bf16(kf[d0 & 1][1], qr[d0], c1, 0, 0, 0); }
;     if (d0 + 2 < NS) KRD_(d0 & 1, d0 + 2);
;     if constexpr (NOMAX) { }
;     else {
; #pragma unroll
;     for (int r = d0 * RPS; r < (d0 + 1) * RPS; ++r) { p1[r] = __builtin_amdgcn_exp2f(p1[r]); psa += p0[r]; }
;     if (d0 > 0) {
; #pragma unroll
;       for (int r = (d0 - 1) * RPS; r < d0 * RPS; ++r) psb += p1[r]; } }
;     if constexpr (NOMAX) {
;       if (d0 == NS / 4 - 1) { PK4R(p0, 0, pa[0]); PIN(pa[0]); }
;       if (d0 == NS / 2 - 1) { PK4R(p0, 8, pa[1]); PIN(pa[1]); }
;       if (d0 == 3 * NS / 4 - 1) { PK4R(p1, 0, pa[2]); PIN(pa[2]); }
;       if (d0 == NS - 1) { PK4R(p1, 8, pa[3]); PIN(pa[3]); }
;     } else {
;     if (d0 == NS / 2 - 1) { PK4R(p0, 0, pa[0]); PIN(pa[0]); }
;     if (d0 == NS / 2) { PK4R(p0, 8, pa[1]); PIN(pa[1]); }
;     if (d0 == NS - 1) { PK4R(p1, 0, pa[2]); PIN(pa[2]); }
;     }
;     if (d0 == NS - 1) {
;       vl[0] = vtr(vp + v_rd_off(0, 0, 0)); vh[0] = vtr(vp + v_rd_off(0, 0, 1)); vl[1] = vtr(vp + v_rd_off(1, 0, 0)); vh[1] = vtr(vp + v_rd_off(1, 0, 1)); }
;     PIN(p1); PIN(psa); PIN(psb);
;     SBAR();
;   }
.LBB0_327:
	v_add_u32_e32 v217, s58, v187
	v_mfma_f32_32x32x16_bf16 v[96:111], v[80:83], v[156:159], 0
	v_add_u32_e32 v212, s18, v207
	ds_read_b128 v[2:5], v212
	ds_read_b128 v[218:221], v212 offset:4096
	v_cvt_pk_bf16_f32 v128, v128, v129
	v_cvt_pk_bf16_f32 v129, v130, v131
	v_cvt_pk_bf16_f32 v130, v132, v133
	v_cvt_pk_bf16_f32 v131, v134, v135
	v_mfma_f32_32x32x16_bf16 v[80:95], v[84:87], v[156:159], 0
	v_permlane32_swap_b32_e32 v128, v130
	v_permlane32_swap_b32_e32 v129, v131
	v_mfma_f32_32x32x16_bf16 v[96:111], v[6:9], v[152:155], v[96:111]
	v_add_u32_e32 v6, s18, v208
	ds_read_b128 v[132:135], v6
	ds_read_b128 v[222:225], v6 offset:4096
	v_mfma_f32_32x32x16_bf16 v[80:95], v[10:13], v[152:155], v[80:95]
	v_cvt_pk_bf16_f32 v10, v136, v137
	v_cvt_pk_bf16_f32 v11, v138, v139
	v_cvt_pk_bf16_f32 v12, v140, v141
	v_cvt_pk_bf16_f32 v13, v142, v143
	s_nop 0
	v_permlane32_swap_b32_e32 v10, v12
	v_permlane32_swap_b32_e32 v11, v13
	s_waitcnt lgkmcnt(3)
	v_mfma_f32_32x32x16_bf16 v[96:111], v[2:5], v[148:151], v[96:111]
	v_cvt_pk_bf16_f32 v6, v112, v113
	v_cvt_pk_bf16_f32 v7, v114, v115
	v_cvt_pk_bf16_f32 v8, v116, v117
	v_cvt_pk_bf16_f32 v9, v118, v119
	s_nop 0
	v_permlane32_swap_b32_e32 v6, v8
	s_waitcnt lgkmcnt(2)
	v_mfma_f32_32x32x16_bf16 v[80:95], v[218:221], v[148:151], v[80:95]
	v_permlane32_swap_b32_e32 v7, v9
	s_nop 0
	v_cvt_pk_bf16_f32 v2, v120, v121
	v_cvt_pk_bf16_f32 v3, v122, v123
	v_cvt_pk_bf16_f32 v4, v124, v125
	v_cvt_pk_bf16_f32 v5, v126, v127
	s_waitcnt lgkmcnt(1)
	v_mfma_f32_32x32x16_bf16 v[96:111], v[132:135], v[144:147], v[96:111]
	v_permlane32_swap_b32_e32 v2, v4
	v_permlane32_swap_b32_e32 v3, v5
	ds_read_b64_tr_b16 v[136:137], v217
	ds_read_b64_tr_b16 v[138:139], v217 offset:2048
	ds_read_b64_tr_b16 v[132:133], v217 offset:512
	ds_read_b64_tr_b16 v[134:135], v217 offset:2560
	s_waitcnt lgkmcnt(4)
	v_mfma_f32_32x32x16_bf16 v[80:95], v[222:225], v[144:147], v[80:95]
	v_subrev_u32_e32 v112, 31, v216
	v_cmp_gt_i32_e32 vcc, s67, v112
	v_mov_b32_e32 v212, v199
	s_and_saveexec_b64 s[4:5], vcc
	s_cbranch_execz .LBB0_331
	v_cmp_ge_i32_e32 vcc, s94, v181
	v_mov_b32_e32 v212, v198
	s_and_saveexec_b64 s[18:19], vcc
	s_cbranch_execz .LBB0_330
	ds_read2_b32 v[112:113], v211 offset0:64 offset1:65
	ds_read2_b32 v[114:115], v211 offset0:66 offset1:67
	ds_read2_b32 v[116:117], v211 offset0:72 offset1:73
	ds_read2_b32 v[118:119], v211 offset0:74 offset1:75
	ds_read2_b32 v[120:121], v211 offset0:80 offset1:81
	ds_read2_b32 v[122:123], v211 offset0:82 offset1:83
	ds_read2_b32 v[124:125], v211 offset0:88 offset1:89
	ds_read2_b32 v[126:127], v211 offset0:90 offset1:91
	ds_read2_b32 v[140:141], v211 offset0:96 offset1:97
	ds_read2_b32 v[142:143], v211 offset0:98 offset1:99
	ds_read2_b32 v[218:219], v211 offset0:104 offset1:105
	ds_read2_b32 v[220:221], v211 offset0:106 offset1:107
	s_waitcnt lgkmcnt(0)
	v_pk_add_f32 v[96:97], v[96:97], v[112:113]
	v_pk_add_f32 v[108:109], v[108:109], v[124:125]
	v_pk_add_f32 v[106:107], v[106:107], v[122:123]
	v_pk_add_f32 v[104:105], v[104:105], v[120:121]
	ds_read2_b32 v[112:113], v211 offset0:112 offset1:113
	ds_read2_b32 v[120:121], v211 offset0:114 offset1:115
	ds_read2_b32 v[122:123], v211 offset0:120 offset1:121
	ds_read2_b32 v[124:125], v211 offset0:122 offset1:123
	v_pk_add_f32 v[110:111], v[110:111], v[126:127]
	v_pk_add_f32 v[102:103], v[102:103], v[118:119]
	v_pk_add_f32 v[100:101], v[100:101], v[116:117]
	v_pk_add_f32 v[98:99], v[98:99], v[114:115]
	v_pk_add_f32 v[80:81], v[80:81], v[140:141]
	s_waitcnt lgkmcnt(0)
	v_pk_add_f32 v[94:95], v[94:95], v[124:125]
	v_pk_add_f32 v[92:93], v[92:93], v[122:123]
	v_pk_add_f32 v[90:91], v[90:91], v[120:121]
	v_pk_add_f32 v[88:89], v[88:89], v[112:113]
	v_pk_add_f32 v[86:87], v[86:87], v[220:221]
	v_pk_add_f32 v[84:85], v[84:85], v[218:219]
	v_pk_add_f32 v[82:83], v[82:83], v[142:143]
	v_mov_b32_e32 v212, 0

; #define SBAR() __builtin_amdgcn_sched_barrier(0)
; #define PIN(x) asm volatile("" : "+v"(x))
; #define VRD_(S, I) do { vl[S] = vtr(vp + v_rd_off((I) & 3, (I) >> 2, 0)); vh[S] = vtr(vp + v_rd_off((I) & 3, (I) >> 2, 1)); } while (0)
; template <int DK, bool NOMAX> ...
;     ...
; #pragma unroll
;   for (int i = 0; i < 16; ++i) {
;     if (i + 2 < 16) VRD_((i + 2) % 3, i + 2);
;     if (i == 1) { if (dk) __builtin_amdgcn_global_load_lds((const unsigned*)gk0, lk, 16, 0, 0); }
;     if (i == 3) { if constexpr (DK == 128) { if (dk) __builtin_amdgcn_global_load_lds((const unsigned*)gk1, (lds_up)((lds_cp)lk + 8192), 16, 0, 0); } }
;     if (i == 5) { if (dv) __builtin_amdgcn_global_load_lds((const unsigned*)gv0, lv, 16, 0, 0); }
;     if (i == 7) { if (dv) __builtin_amdgcn_global_load_lds((const unsigned*)gv1, (lds_up)((lds_cp)lv + 8192), 16, 0, 0); }
;     if (i == 12 || i == 13) { const int cb_ = ((i - 12) * 16 + hi * 8) * 2;
;       if constexpr (DK == 128) { kf[i - 12][0] = *reinterpret_cast<const bf16x8*>(Kn + KSWZ128(r32, cb_)); kf[i - 12][1] = *reinterpret_cast<const bf16x8*>(Kn + KSWZ128(32 + r32, cb_)); }
;       else { kf[i - 12][0] = *reinterpret_cast<const bf16x8*>(Kn + KSWZ64(r32, cb_)); kf[i - 12][1] = *reinterpret_cast<const bf16x8*>(Kn + KSWZ64(32 + r32, cb_)); } }
;     SBAR();
;     o[i & 3] = __builtin_amdgcn_mfma_f32_32x32x16_bf16(pa[i >> 2], VFR_(i % 3), o[i & 3], 0, 0, 0);
;     if constexpr (NOMAX) { c0[i] = __builtin_amdgcn_exp2f(c0[i]); c1[i] = __builtin_amdgcn_exp2f(c1[i]); if (i > 0) { psa += c0[i - 1]; psb += c1[i - 1]; } PIN(c0); PIN(c1); PIN(psa); PIN(psb); }
.LBB0_331:
	s_or_b64 exec, exec, s[4:5]
	s_cmp_gt_u32 s96, 59
	s_cselect_b64 s[4:5], -1, 0
	ds_read_b64_tr_b16 v[112:113], v217 offset:1024
	ds_read_b64_tr_b16 v[114:115], v217 offset:3072
	s_waitcnt lgkmcnt(4)
	v_mfma_f32_32x32x16_bf16 v[16:31], v[128:131], v[136:139], v[16:31]
	v_exp_f32_e32 v96, v96
	v_exp_f32_e32 v80, v80
	ds_read_b64_tr_b16 v[116:117], v217 offset:1536
	ds_read_b64_tr_b16 v[118:119], v217 offset:3584
	s_and_b64 vcc, exec, s[4:5]
	s_cbranch_vccnz .LBB0_333
	v_lshl_add_u64 v[124:125], v[164:165], 0, s[34:35]
	s_add_i32 m0, s3, s59
	s_nop 0
	global_load_lds_dwordx4 v[124:125], off
; template <int DK, bool NOMAX> ...
;     ...
; #pragma unroll
;   for (int i = 0; i < 16; ++i) {
;     if (i + 2 < 16) VRD_((i + 2) % 3, i + 2);
;     if (i == 1) { if (dk) __builtin_amdgcn_global_load_lds((const unsigned*)gk0, lk, 16, 0, 0); }
;     if (i == 3) { if constexpr (DK == 128) { if (dk) __builtin_amdgcn_global_load_lds((const unsigned*)gk1, (lds_up)((lds_cp)lk + 8192), 16, 0, 0); } }
;     if (i == 5) { if (dv) __builtin_amdgcn_global_load_lds((const unsigned*)gv0, lv, 16, 0, 0); }
;     if (i == 7) { if (dv) __builtin_amdgcn_global_load_lds((const unsigned*)gv1, (lds_up)((lds_cp)lv + 8192), 16, 0, 0); }
;     if (i == 12 || i == 13) { const int cb_ = ((i - 12) * 16 + hi * 8) * 2;
;       if constexpr (DK == 128) { kf[i - 12][0] = *reinterpret_cast<const bf16x8*>(Kn + KSWZ128(r32, cb_)); kf[i - 12][1] = *reinterpret_cast<const bf16x8*>(Kn + KSWZ128(32 + r32, cb_)); }
;       else { kf[i - 12][0] = *reinterpret_cast<const bf16x8*>(Kn + KSWZ64(r32, cb_)); kf[i - 12][1] = *reinterpret_cast<const bf16x8*>(Kn + KSWZ64(32 + r32, cb_)); } }
;     SBAR();
;     o[i & 3] = __builtin_amdgcn_mfma_f32_32x32x16_bf16(pa[i >> 2], VFR_(i % 3), o[i & 3], 0, 0, 0);
;     if constexpr (NOMAX) { c0[i] = __builtin_amdgcn_exp2f(c0[i]); c1[i] = __builtin_amdgcn_exp2f(c1[i]); if (i > 0) { psa += c0[i - 1]; psb += c1[i - 1]; } PIN(c0); PIN(c1); PIN(psa); PIN(psb); }
;     else {
;     if (i == 0) { ma = max3f(c0[0], c0[1], c1[0]); mb = max3f(c0[2], c0[3], c1[1]); ma = max3f(ma, c1[2], c1[3]); }
;     if (i >= 1 && i <= 3) { const int r = 4 * i; ma = max3f(ma, c0[r], c0[r + 1]); mb = max3f(mb, c0[r + 2], c0[r + 3]); ma = max3f(ma, c1[r], c1[r + 1]); mb = max3f(mb, c1[r + 2], c1[r + 3]); }
;     if (i == 4) { float pmax = fmaxf(ma, mb);
;       { auto rr = __builtin_amdgcn_permlane32_swap(__float_as_uint(pmax), __float_as_uint(pmax), false, false);
;         pmax = fmaxf(__uint_as_float(rr[0]), __uint_as_float(rr[1])); }
;       pmax += cb;
;       const bool keep = __all(pmax - m_reg <= THR2);
;       const float mn = keep ? m_reg : fmaxf(m_reg, pmax);
;       alpha = __builtin_amdgcn_exp2f(m_reg - mn); m_reg = mn; mnC = cb - mn; }
;     if (i >= 5 && i <= 8) { const int r = 4 * (i - 5);
; #pragma unroll
;       for (int q = 0; q < 4; ++q) { c0[r + q] += mnC; c1[r + q] += mnC; } }
;     if (i >= 9) { const int r0 = (i - 9) * 2 + (i > 14 ? 1 : 0), n = i >= 14 ? 3 : 2;
.LBB0_333:
	v_sub_f32_e32 v120, v215, v212
	v_exp_f32_e32 v120, v120
	s_add_i32 s18, s63, 0xffffc000
	s_and_b32 s18, s18, 0xc000
	s_add_i32 s18, s18, 0
	v_lshl_add_u64 v[126:127], v[166:167], 0, s[36:37]
	v_lshl_add_u64 v[136:137], v[168:169], 0, s[36:37]
	s_waitcnt lgkmcnt(4)
	v_mfma_f32_32x32x16_bf16 v[32:47], v[128:131], v[132:135], v[32:47]
	v_exp_f32_e32 v97, v97
	v_exp_f32_e32 v81, v81
	ds_read_b64_tr_b16 v[122:123], v217 offset:4096
	ds_read_b64_tr_b16 v[124:125], v217 offset:6144
	s_waitcnt lgkmcnt(4)
	v_mfma_f32_32x32x16_bf16 v[48:63], v[128:131], v[112:115], v[48:63]
	v_exp_f32_e32 v98, v98
	v_exp_f32_e32 v82, v82
	v_add_f32_e32 v132, v81, v80
	v_add_f32_e32 v121, v97, v96
	ds_read_b64_tr_b16 v[112:113], v217 offset:4608
	ds_read_b64_tr_b16 v[114:115], v217 offset:6656
	s_waitcnt lgkmcnt(4)
	v_mfma_f32_32x32x16_bf16 v[64:79], v[128:131], v[116:119], v[64:79]
	v_exp_f32_e32 v99, v99
	v_exp_f32_e32 v83, v83
	v_add_f32_e32 v128, v82, v132
	v_add_f32_e32 v121, v98, v121
	ds_read_b64_tr_b16 v[116:117], v217 offset:5120
	ds_read_b64_tr_b16 v[118:119], v217 offset:7168
	s_waitcnt lgkmcnt(4)
	v_mfma_f32_32x32x16_bf16 v[16:31], v[10:13], v[122:125], v[16:31]
	v_exp_f32_e32 v100, v100
	v_exp_f32_e32 v84, v84
	v_add_f32_e32 v128, v83, v128
	v_add_f32_e32 v121, v99, v121
	s_add_i32 s19, s62, s95
	s_mov_b32 m0, s19
	ds_read_b64_tr_b16 v[122:123], v217 offset:5632
	ds_read_b64_tr_b16 v[124:125], v217 offset:7680
	global_load_lds_dwordx4 v[126:127], off
	s_waitcnt lgkmcnt(4)
	v_mfma_f32_32x32x16_bf16 v[32:47], v[10:13], v[112:115], v[32:47]
	v_exp_f32_e32 v101, v101
	v_exp_f32_e32 v85, v85
	v_add_f32_e32 v126, v84, v128
	v_add_f32_e32 v121, v100, v121
	ds_read_b64_tr_b16 v[112:113], v217 offset:8192
	ds_read_b64_tr_b16 v[114:115], v217 offset:10240
	s_waitcnt lgkmcnt(4)
	v_mfma_f32_32x32x16_bf16 v[48:63], v[10:13], v[116:119], v[48:63]
	v_exp_f32_e32 v102, v102
	v_exp_f32_e32 v86, v86
	v_add_f32_e32 v126, v85, v126
	v_add_f32_e32 v121, v101, v121
	s_add_i32 m0, s19, 0x2000
	ds_read_b64_tr_b16 v[116:117], v217 offset:8704
	ds_read_b64_tr_b16 v[118:119], v217 offset:10752
	global_load_lds_dwordx4 v[136:137], off
	s_waitcnt lgkmcnt(4)
	v_mfma_f32_32x32x16_bf16 v[64:79], v[10:13], v[122:125], v[64:79]
	v_exp_f32_e32 v103, v103
	v_exp_f32_e32 v87, v87
	v_add_f32_e32 v122, v86, v126
	v_add_f32_e32 v121, v102, v121
	ds_read_b64_tr_b16 v[10:11], v217 offset:9216
	ds_read_b64_tr_b16 v[12:13], v217 offset:11264
	s_waitcnt lgkmcnt(4)
	v_mfma_f32_32x32x16_bf16 v[16:31], v[6:9], v[112:115], v[16:31]
	v_exp_f32_e32 v104, v104
	v_exp_f32_e32 v88, v88
	v_add_f32_e32 v122, v87, v122
	v_add_f32_e32 v121, v103, v121
	ds_read_b64_tr_b16 v[112:113], v217 offset:9728
	ds_read_b64_tr_b16 v[114:115], v217 offset:11776
	s_waitcnt lgkmcnt(4)
	v_mfma_f32_32x32x16_bf16 v[32:47], v[6:9], v[116:119], v[32:47]
	v_exp_f32_e32 v105, v105
	v_exp_f32_e32 v89, v89
	v_add_f32_e32 v116, v88, v122
	v_add_f32_e32 v117, v104, v121
	ds_read_b64_tr_b16 v[122:123], v217 offset:12288
	ds_read_b64_tr_b16 v[124:125], v217 offset:14336
	s_waitcnt lgkmcnt(4)
	v_mfma_f32_32x32x16_bf16 v[48:63], v[6:9], v[10:13], v[48:63]
	v_exp_f32_e32 v106, v106
	v_exp_f32_e32 v90, v90
	v_add_f32_e32 v10, v89, v116
	v_add_f32_e32 v11, v105, v117
	ds_read_b64_tr_b16 v[126:127], v217 offset:12800
	ds_read_b64_tr_b16 v[128:129], v217 offset:14848
	s_waitcnt lgkmcnt(4)
	v_mfma_f32_32x32x16_bf16 v[64:79], v[6:9], v[112:115], v[64:79]
	v_exp_f32_e32 v107, v107
	v_exp_f32_e32 v91, v91
	v_add_f32_e32 v6, v90, v10
	v_add_f32_e32 v7, v106, v11
	v_add_u32_e32 v8, s18, v209
	ds_read_b64_tr_b16 v[130:131], v217 offset:13312
	ds_read_b64_tr_b16 v[132:133], v217 offset:15360
	ds_read_b128 v[116:119], v8
	ds_read_b128 v[112:115], v8 offset:4096
	s_waitcnt lgkmcnt(6)
	v_mfma_f32_32x32x16_bf16 v[16:31], v[2:5], v[122:125], v[16:31]
	v_exp_f32_e32 v108, v108
	v_exp_f32_e32 v92, v92
	v_add_f32_e32 v121, v91, v6
	v_add_f32_e32 v134, v107, v7
	v_add_u32_e32 v6, s18, v210
	ds_read_b64_tr_b16 v[122:123], v217 offset:13824
	ds_read_b64_tr_b16 v[124:125], v217 offset:15872
	ds_read_b128 v[10:13], v6
	ds_read_b128 v[6:9], v6 offset:4096
	s_waitcnt lgkmcnt(8)
	v_mfma_f32_32x32x16_bf16 v[32:47], v[2:5], v[126:129], v[32:47]
	v_exp_f32_e32 v109, v109
	v_exp_f32_e32 v93, v93
	v_add_f32_e32 v121, v92, v121
	v_add_f32_e32 v126, v108, v134
	s_waitcnt lgkmcnt(6)
	v_mfma_f32_32x32x16_bf16 v[48:63], v[2:5], v[130:133], v[48:63]
	v_exp_f32_e32 v110, v110
	v_exp_f32_e32 v94, v94
	v_add_f32_e32 v121, v93, v121
	v_add_f32_e32 v126, v109, v126
	s_waitcnt lgkmcnt(2)
	v_mfma_f32_32x32x16_bf16 v[64:79], v[2:5], v[122:125], v[64:79]
	v_exp_f32_e32 v111, v111
	v_exp_f32_e32 v95, v95
	v_add_f32_e32 v2, v94, v121
	v_add_f32_e32 v3, v110, v126
	s_nop 0
	v_add_f32_e32 v3, v111, v3
	v_add_f32_e32 v2, v95, v2
	v_add_f32_e32 v2, v3, v2
	v_mov_b32_e32 v3, v2
	s_nop 1
	v_permlane32_swap_b32_e32 v2, v3
	v_cmp_neq_f32_e32 vcc, 1.0, v120
	s_cbranch_vccz .LBB0_337
	s_and_saveexec_b64 s[18:19], s[46:47]
	ds_write_b32 v188, v120 offset:128
	s_or_b64 exec, exec, s[18:19]
	s_waitcnt lgkmcnt(0)
	v_add_u32_e32 v4, s2, v170
	ds_read_b128 v[122:125], v4 offset:224
	ds_read_b128 v[126:129], v4 offset:192
	ds_read_b128 v[130:133], v4 offset:160
	ds_read_b128 v[134:137], v4 offset:128
	s_waitcnt lgkmcnt(0)
	v_pk_mul_f32 v[28:29], v[28:29], v[122:123]
	v_pk_mul_f32 v[24:25], v[24:25], v[126:127]
	v_pk_mul_f32 v[20:21], v[20:21], v[130:131]
	v_pk_mul_f32 v[30:31], v[30:31], v[124:125]
	v_pk_mul_f32 v[26:27], v[26:27], v[128:129]
	v_pk_mul_f32 v[22:23], v[22:23], v[132:133]
	v_pk_mul_f32 v[18:19], v[18:19], v[136:137]
	v_pk_mul_f32 v[16:17], v[16:17], v[134:135]
	v_pk_mul_f32 v[44:45], v[44:45], v[122:123]
	v_pk_mul_f32 v[40:41], v[40:41], v[126:127]
	v_pk_mul_f32 v[36:37], v[36:37], v[130:131]
	v_pk_mul_f32 v[46:47], v[46:47], v[124:125]
	v_pk_mul_f32 v[42:43], v[42:43], v[128:129]
	v_pk_mul_f32 v[38:39], v[38:39], v[132:133]
	v_pk_mul_f32 v[34:35], v[34:35], v[136:137]
	v_pk_mul_f32 v[32:33], v[32:33], v[134:135]
	v_pk_mul_f32 v[60:61], v[60:61], v[122:123]
	v_pk_mul_f32 v[56:57], v[56:57], v[126:127]
	v_pk_mul_f32 v[52:53], v[52:53], v[130:131]
	v_pk_mul_f32 v[62:63], v[62:63], v[124:125]
	v_pk_mul_f32 v[58:59], v[58:59], v[128:129]
	v_pk_mul_f32 v[54:55], v[54:55], v[132:133]
	v_pk_mul_f32 v[50:51], v[50:51], v[136:137]
	v_pk_mul_f32 v[48:49], v[48:49], v[134:135]
	v_pk_mul_f32 v[76:77], v[76:77], v[122:123]
	v_pk_mul_f32 v[72:73], v[72:73], v[126:127]
	v_pk_mul_f32 v[68:69], v[68:69], v[130:131]
	v_pk_mul_f32 v[78:79], v[78:79], v[124:125]
	v_pk_mul_f32 v[74:75], v[74:75], v[128:129]
	v_pk_mul_f32 v[70:71], v[70:71], v[132:133]
	v_pk_mul_f32 v[66:67], v[66:67], v[136:137]
	v_pk_mul_f32 v[64:65], v[64:65], v[134:135]

; #define SBAR() __builtin_amdgcn_sched_barrier(0)
; #define PIN(x) asm volatile("" : "+v"(x))
; template <int DK, bool NOMAX> ...
;     ...
;   float psa = 0.f, psb = 0.f;
;   SBAR();
; #pragma unroll
;   for (int d0 = 0; d0 < NS; ++d0) {
;     if (d0 == 0) { c0 = __builtin_amdgcn_mfma_f32_32x32x16_bf16(kf[0][0], qr[0], f32x16{}, 0, 0, 0); c1 = __builtin_amdgcn_mfma_f32_32x32x16_bf16(kf[0][1], qr[0], f32x16{}, 0, 0, 0); }
;     else { c0 = __builtin_amdgcn_mfma_f32_32x32x16_bf16(kf[d0 & 1][0], qr[d0], c0, 0, 0, 0); c1 = __builtin_amdgcn_mfma_f32_32x32x16_bf16(kf[d0 & 1][1], qr[d0], c1, 0, 0, 0); }
;     if (d0 + 2 < NS) KRD_(d0 & 1, d0 + 2);
;     if constexpr (NOMAX) { }
;     else {
; #pragma unroll
;     for (int r = d0 * RPS; r < (d0 + 1) * RPS; ++r) { p1[r] = __builtin_amdgcn_exp2f(p1[r]); psa += p0[r]; }
;     if (d0 > 0) {
; #pragma unroll
;       for (int r = (d0 - 1) * RPS; r < d0 * RPS; ++r) psb += p1[r]; } }
;     if constexpr (NOMAX) {
;       if (d0 == NS / 4 - 1) { PK4R(p0, 0, pa[0]); PIN(pa[0]); }
;       if (d0 == NS / 2 - 1) { PK4R(p0, 8, pa[1]); PIN(pa[1]); }
;       if (d0 == 3 * NS / 4 - 1) { PK4R(p1, 0, pa[2]); PIN(pa[2]); }
;       if (d0 == NS - 1) { PK4R(p1, 8, pa[3]); PIN(pa[3]); }
;     } else {
;     if (d0 == NS / 2 - 1) { PK4R(p0, 0, pa[0]); PIN(pa[0]); }
;     if (d0 == NS / 2) { PK4R(p0, 8, pa[1]); PIN(pa[1]); }
;     if (d0 == NS - 1) { PK4R(p1, 0, pa[2]); PIN(pa[2]); }
;     }
;     if (d0 == NS - 1) {
;       vl[0] = vtr(vp + v_rd_off(0, 0, 0)); vh[0] = vtr(vp + v_rd_off(0, 0, 1)); vl[1] = vtr(vp + v_rd_off(1, 0, 0)); vh[1] = vtr(vp + v_rd_off(1, 0, 1)); }
;     PIN(p1); PIN(psa); PIN(psb);
;     SBAR();
;   }
; template <int DK, bool NOMAX> ...
;     ...
; #pragma unroll
;   for (int i = 0; i < 16; ++i) {
;     if (i + 2 < 16) VRD_((i + 2) % 3, i + 2);
;     if (i == 1) { if (dk) __builtin_amdgcn_global_load_lds((const unsigned*)gk0, lk, 16, 0, 0); }
;     if (i == 3) { if constexpr (DK == 128) { if (dk) __builtin_amdgcn_global_load_lds((const unsigned*)gk1, (lds_up)((lds_cp)lk + 8192), 16, 0, 0); } }
;     if (i == 5) { if (dv) __builtin_amdgcn_global_load_lds((const unsigned*)gv0, lv, 16, 0, 0); }
;     if (i == 7) { if (dv) __builtin_amdgcn_global_load_lds((const unsigned*)gv1, (lds_up)((lds_cp)lv + 8192), 16, 0, 0); }
;     if (i == 12 || i == 13) { const int cb_ = ((i - 12) * 16 + hi * 8) * 2;
.LBB0_402:
	s_mov_b32 s17, s14
	s_mov_b32 s14, s8
	s_add_i32 s8, s18, 0xffffc000
	s_and_b32 s38, s8, 0xc000
	s_add_i32 s8, s38, 0
	v_add_u32_e32 v0, s14, v204
	s_waitcnt lgkmcnt(0)
	v_mfma_f32_32x32x16_bf16 v[114:129], v[102:105], v[158:161], 0
	v_add_u32_e32 v188, s8, v218
	ds_read_b128 v[184:187], v188
	ds_read_b128 v[188:191], v188 offset:8192
	v_mfma_f32_32x32x16_bf16 v[98:113], v[98:101], v[158:161], 0
	v_mfma_f32_32x32x16_bf16 v[114:129], v[166:169], v[154:157], v[114:129]
	v_mfma_f32_32x32x16_bf16 v[98:113], v[162:165], v[154:157], v[98:113]
	v_add_u32_e32 v162, s8, v219
	ds_read_b128 v[166:169], v162
	ds_read_b128 v[226:229], v162 offset:8192
	v_cvt_pk_bf16_f32 v162, v82, v83
	v_cvt_pk_bf16_f32 v163, v84, v85
	v_cvt_pk_bf16_f32 v164, v86, v87
	v_cvt_pk_bf16_f32 v165, v88, v89
	s_nop 0
	v_permlane32_swap_b32_e32 v162, v164
	v_permlane32_swap_b32_e32 v163, v165
	s_waitcnt lgkmcnt(3)
	v_mfma_f32_32x32x16_bf16 v[114:129], v[184:187], v[150:153], v[114:129]
	v_add_u32_e32 v86, s8, v220
	ds_read_b128 v[82:85], v86
	ds_read_b128 v[86:89], v86 offset:8192
	s_waitcnt lgkmcnt(4)
	v_mfma_f32_32x32x16_bf16 v[98:113], v[188:191], v[150:153], v[98:113]
	s_waitcnt lgkmcnt(3)
	v_mfma_f32_32x32x16_bf16 v[114:129], v[166:169], v[146:149], v[114:129]
	v_add_u32_e32 v184, s8, v221
	ds_read_b128 v[166:169], v184
	ds_read_b128 v[184:187], v184 offset:8192
	v_cvt_pk_bf16_f32 v90, v90, v91
	v_cvt_pk_bf16_f32 v91, v92, v93
	v_cvt_pk_bf16_f32 v92, v94, v95
	v_cvt_pk_bf16_f32 v93, v96, v97
	s_waitcnt lgkmcnt(4)
	v_mfma_f32_32x32x16_bf16 v[98:113], v[226:229], v[146:149], v[98:113]
	v_permlane32_swap_b32_e32 v90, v92
	v_permlane32_swap_b32_e32 v91, v93
	s_waitcnt lgkmcnt(3)
	v_mfma_f32_32x32x16_bf16 v[114:129], v[82:85], v[142:145], v[114:129]
	s_waitcnt lgkmcnt(2)
	v_mfma_f32_32x32x16_bf16 v[98:113], v[86:89], v[142:145], v[98:113]
	v_add_u32_e32 v86, s8, v222
	ds_read_b128 v[82:85], v86
	ds_read_b128 v[94:97], v86 offset:8192
	s_waitcnt lgkmcnt(3)
	v_mfma_f32_32x32x16_bf16 v[114:129], v[166:169], v[138:141], v[114:129]
	v_add_u32_e32 v86, s8, v223
	s_waitcnt lgkmcnt(2)
	v_mfma_f32_32x32x16_bf16 v[98:113], v[184:187], v[138:141], v[98:113]
	ds_read_b128 v[166:169], v86
	ds_read_b128 v[184:187], v86 offset:8192
	v_cvt_pk_bf16_f32 v86, v66, v67
	v_cvt_pk_bf16_f32 v87, v68, v69
	v_cvt_pk_bf16_f32 v88, v70, v71
	v_cvt_pk_bf16_f32 v89, v72, v73
	s_nop 0
	v_permlane32_swap_b32_e32 v86, v88
	v_permlane32_swap_b32_e32 v87, v89
	s_waitcnt lgkmcnt(3)
	v_mfma_f32_32x32x16_bf16 v[114:129], v[82:85], v[130:133], v[114:129]
	s_waitcnt lgkmcnt(2)
	v_mfma_f32_32x32x16_bf16 v[98:113], v[94:97], v[130:133], v[98:113]
	v_cvt_pk_bf16_f32 v82, v74, v75
	v_cvt_pk_bf16_f32 v83, v76, v77
	v_cvt_pk_bf16_f32 v84, v78, v79
	v_cvt_pk_bf16_f32 v85, v80, v81
	s_waitcnt lgkmcnt(1)
	v_mfma_f32_32x32x16_bf16 v[114:129], v[166:169], v[134:137], v[114:129]
	v_permlane32_swap_b32_e32 v82, v84
	v_permlane32_swap_b32_e32 v83, v85
	ds_read_b64_tr_b16 v[166:167], v0
	ds_read_b64_tr_b16 v[168:169], v0 offset:2048
	ds_read_b64_tr_b16 v[94:95], v0 offset:512
	ds_read_b64_tr_b16 v[96:97], v0 offset:2560
	s_waitcnt lgkmcnt(4)
	v_mfma_f32_32x32x16_bf16 v[98:113], v[184:187], v[134:137], v[98:113]
	s_cmpk_lt_u32 s15, 0x7d
	s_cselect_b64 s[10:11], -1, 0
	s_cmpk_gt_u32 s15, 0x7c
	s_cselect_b64 s[8:9], -1, 0
	s_add_i32 s19, s18, 0x8000
	s_and_b32 s12, s19, 0xc000
	ds_read_b64_tr_b16 v[70:71], v0 offset:1024
	ds_read_b64_tr_b16 v[72:73], v0 offset:3072
	s_waitcnt lgkmcnt(4)
	v_mfma_f32_32x32x16_bf16 v[50:65], v[162:165], v[166:169], v[50:65]
	v_exp_f32_e32 v114, v114
	s_nop 0
	v_exp_f32_e32 v98, v98
	ds_read_b64_tr_b16 v[66:67], v0 offset:1536
	ds_read_b64_tr_b16 v[68:69], v0 offset:3584
	s_and_b64 vcc, exec, s[8:9]
	v_lshl_add_u64 v[186:187], s[0:1], 0, v[182:183]
	s_cbranch_vccnz .LBB0_404
	v_lshl_add_u64 v[76:77], v[186:187], 0, s[50:51]
	s_add_i32 m0, s2, s12
	s_nop 0
	global_load_lds_dwordx4 v[76:77], off
.LBB0_404:
	v_lshl_add_u64 v[184:185], s[0:1], 0, v[180:181]
	s_waitcnt lgkmcnt(4)
	v_mfma_f32_32x32x16_bf16 v[34:49], v[162:165], v[94:97], v[34:49]
	v_exp_f32_e32 v115, v115
	v_exp_f32_e32 v99, v99
	ds_read_b64_tr_b16 v[74:75], v0 offset:4096
	ds_read_b64_tr_b16 v[76:77], v0 offset:6144
	s_waitcnt lgkmcnt(4)
	v_mfma_f32_32x32x16_bf16 v[18:33], v[162:165], v[70:73], v[18:33]
	v_exp_f32_e32 v116, v116
	v_exp_f32_e32 v100, v100
	v_add_f32_e32 v79, v99, v98
	v_add_f32_e32 v78, v115, v114
	ds_read_b64_tr_b16 v[70:71], v0 offset:4608
	ds_read_b64_tr_b16 v[72:73], v0 offset:6656
	s_andn2_b64 vcc, exec, s[10:11]
	s_cbranch_vccnz .LBB0_406
	s_add_i32 s10, s2, s12
	v_lshl_add_u64 v[80:81], v[184:185], 0, s[50:51]
	s_add_i32 m0, s10, 0x2000
	s_nop 0
	global_load_lds_dwordx4 v[80:81], off

; #define SBAR() __builtin_amdgcn_sched_barrier(0)
; #define PIN(x) asm volatile("" : "+v"(x))
; template <int DK, bool NOMAX> ...
;     ...
;   float psa = 0.f, psb = 0.f;
;   SBAR();
; #pragma unroll
;   for (int d0 = 0; d0 < NS; ++d0) {
;     if (d0 == 0) { c0 = __builtin_amdgcn_mfma_f32_32x32x16_bf16(kf[0][0], qr[0], f32x16{}, 0, 0, 0); c1 = __builtin_amdgcn_mfma_f32_32x32x16_bf16(kf[0][1], qr[0], f32x16{}, 0, 0, 0); }
;     else { c0 = __builtin_amdgcn_mfma_f32_32x32x16_bf16(kf[d0 & 1][0], qr[d0], c0, 0, 0, 0); c1 = __builtin_amdgcn_mfma_f32_32x32x16_bf16(kf[d0 & 1][1], qr[d0], c1, 0, 0, 0); }
;     if (d0 + 2 < NS) KRD_(d0 & 1, d0 + 2);
;     if constexpr (NOMAX) { }
;     else {
; #pragma unroll
;     for (int r = d0 * RPS; r < (d0 + 1) * RPS; ++r) { p1[r] = __builtin_amdgcn_exp2f(p1[r]); psa += p0[r]; }
;     if (d0 > 0) {
; #pragma unroll
;       for (int r = (d0 - 1) * RPS; r < d0 * RPS; ++r) psb += p1[r]; } }
;     if constexpr (NOMAX) {
;       if (d0 == NS / 4 - 1) { PK4R(p0, 0, pa[0]); PIN(pa[0]); }
;       if (d0 == NS / 2 - 1) { PK4R(p0, 8, pa[1]); PIN(pa[1]); }
;       if (d0 == 3 * NS / 4 - 1) { PK4R(p1, 0, pa[2]); PIN(pa[2]); }
;       if (d0 == NS - 1) { PK4R(p1, 8, pa[3]); PIN(pa[3]); }
;     } else {
;     if (d0 == NS / 2 - 1) { PK4R(p0, 0, pa[0]); PIN(pa[0]); }
;     if (d0 == NS / 2) { PK4R(p0, 8, pa[1]); PIN(pa[1]); }
;     if (d0 == NS - 1) { PK4R(p1, 0, pa[2]); PIN(pa[2]); }
;     }
;     if (d0 == NS - 1) {
;       vl[0] = vtr(vp + v_rd_off(0, 0, 0)); vh[0] = vtr(vp + v_rd_off(0, 0, 1)); vl[1] = vtr(vp + v_rd_off(1, 0, 0)); vh[1] = vtr(vp + v_rd_off(1, 0, 1)); }
;     PIN(p1); PIN(psa); PIN(psb);
;     SBAR();
;   }
; template <int DK, bool NOMAX> ...
;     ...
; #pragma unroll
;   for (int i = 0; i < 16; ++i) {
;     if (i + 2 < 16) VRD_((i + 2) % 3, i + 2);
;     if (i == 1) { if (dk) __builtin_amdgcn_global_load_lds((const unsigned*)gk0, lk, 16, 0, 0); }
;     if (i == 3) { if constexpr (DK == 128) { if (dk) __builtin_amdgcn_global_load_lds((const unsigned*)gk1, (lds_up)((lds_cp)lk + 8192), 16, 0, 0); } }
;     if (i == 5) { if (dv) __builtin_amdgcn_global_load_lds((const unsigned*)gv0, lv, 16, 0, 0); }
;     if (i == 7) { if (dv) __builtin_amdgcn_global_load_lds((const unsigned*)gv1, (lds_up)((lds_cp)lv + 8192), 16, 0, 0); }
;     if (i == 12 || i == 13) { const int cb_ = ((i - 12) * 16 + hi * 8) * 2;
.LBB0_410:
	v_add_u32_e32 v227, s17, v204
	v_mfma_f32_32x32x16_bf16 v[82:97], v[66:69], v[158:161], 0
	v_add_u32_e32 v232, s12, v218
	ds_read_b128 v[228:231], v232
	ds_read_b128 v[232:235], v232 offset:8192
	v_mfma_f32_32x32x16_bf16 v[66:81], v[70:73], v[158:161], 0
	v_mfma_f32_32x32x16_bf16 v[82:97], v[162:165], v[154:157], v[82:97]
	v_add_u32_e32 v162, s12, v219
	v_mfma_f32_32x32x16_bf16 v[66:81], v[166:169], v[154:157], v[66:81]
	ds_read_b128 v[166:169], v162
	ds_read_b128 v[236:239], v162 offset:8192
	v_cvt_pk_bf16_f32 v162, v114, v115
	v_cvt_pk_bf16_f32 v163, v116, v117
	v_cvt_pk_bf16_f32 v164, v118, v119
	v_cvt_pk_bf16_f32 v165, v120, v121
	s_nop 0
	v_permlane32_swap_b32_e32 v162, v164
	v_permlane32_swap_b32_e32 v163, v165
	s_waitcnt lgkmcnt(3)
	v_mfma_f32_32x32x16_bf16 v[82:97], v[228:231], v[150:153], v[82:97]
	v_add_u32_e32 v118, s12, v220
	ds_read_b128 v[114:117], v118
	ds_read_b128 v[118:121], v118 offset:8192
	s_waitcnt lgkmcnt(4)
	v_mfma_f32_32x32x16_bf16 v[66:81], v[232:235], v[150:153], v[66:81]
	s_waitcnt lgkmcnt(3)
	v_mfma_f32_32x32x16_bf16 v[82:97], v[166:169], v[146:149], v[82:97]
	v_add_u32_e32 v228, s12, v221
	ds_read_b128 v[166:169], v228
	ds_read_b128 v[228:231], v228 offset:8192
	v_cvt_pk_bf16_f32 v122, v122, v123
	v_cvt_pk_bf16_f32 v123, v124, v125
	v_cvt_pk_bf16_f32 v124, v126, v127
	v_cvt_pk_bf16_f32 v125, v128, v129
	s_waitcnt lgkmcnt(4)
	v_mfma_f32_32x32x16_bf16 v[66:81], v[236:239], v[146:149], v[66:81]
	v_permlane32_swap_b32_e32 v122, v124
	v_permlane32_swap_b32_e32 v123, v125
	s_waitcnt lgkmcnt(3)
	v_mfma_f32_32x32x16_bf16 v[82:97], v[114:117], v[142:145], v[82:97]
	s_waitcnt lgkmcnt(2)
	v_mfma_f32_32x32x16_bf16 v[66:81], v[118:121], v[142:145], v[66:81]
	v_add_u32_e32 v118, s12, v222
	ds_read_b128 v[114:117], v118
	ds_read_b128 v[126:129], v118 offset:8192
	s_waitcnt lgkmcnt(3)
	v_mfma_f32_32x32x16_bf16 v[82:97], v[166:169], v[138:141], v[82:97]
	v_add_u32_e32 v118, s12, v223
	s_waitcnt lgkmcnt(2)
	v_mfma_f32_32x32x16_bf16 v[66:81], v[228:231], v[138:141], v[66:81]
	ds_read_b128 v[166:169], v118
	ds_read_b128 v[228:231], v118 offset:8192
	v_cvt_pk_bf16_f32 v118, v98, v99
	v_cvt_pk_bf16_f32 v119, v100, v101
	v_cvt_pk_bf16_f32 v120, v102, v103
	v_cvt_pk_bf16_f32 v121, v104, v105
	s_nop 0
	v_permlane32_swap_b32_e32 v118, v120
	v_permlane32_swap_b32_e32 v119, v121
	s_waitcnt lgkmcnt(3)
	v_mfma_f32_32x32x16_bf16 v[82:97], v[114:117], v[130:133], v[82:97]
	s_waitcnt lgkmcnt(2)
	v_mfma_f32_32x32x16_bf16 v[66:81], v[126:129], v[130:133], v[66:81]
	v_cvt_pk_bf16_f32 v114, v106, v107
	v_cvt_pk_bf16_f32 v115, v108, v109
	v_cvt_pk_bf16_f32 v116, v110, v111
	v_cvt_pk_bf16_f32 v117, v112, v113
	s_waitcnt lgkmcnt(1)
	v_mfma_f32_32x32x16_bf16 v[82:97], v[166:169], v[134:137], v[82:97]
	v_permlane32_swap_b32_e32 v114, v116
	v_permlane32_swap_b32_e32 v115, v117
	ds_read_b64_tr_b16 v[166:167], v227
	ds_read_b64_tr_b16 v[168:169], v227 offset:2048
	ds_read_b64_tr_b16 v[126:127], v227 offset:512
	ds_read_b64_tr_b16 v[128:129], v227 offset:2560
	s_waitcnt lgkmcnt(4)
	v_mfma_f32_32x32x16_bf16 v[66:81], v[228:231], v[134:137], v[66:81]
	s_cmpk_lt_u32 s15, 0x7c
	s_cselect_b64 s[12:13], -1, 0
	s_cmpk_gt_u32 s15, 0x7b
	s_cselect_b64 s[10:11], -1, 0
	ds_read_b64_tr_b16 v[102:103], v227 offset:1024
	ds_read_b64_tr_b16 v[104:105], v227 offset:3072
	s_waitcnt lgkmcnt(4)
	v_mfma_f32_32x32x16_bf16 v[50:65], v[162:165], v[166:169], v[50:65]
	v_exp_f32_e32 v82, v82
	s_nop 2
	v_exp_f32_e32 v66, v66
	ds_read_b64_tr_b16 v[98:99], v227 offset:1536
	ds_read_b64_tr_b16 v[100:101], v227 offset:3584
	s_and_b64 vcc, exec, s[10:11]
	s_cbranch_vccnz .LBB0_412
	v_lshl_add_u64 v[108:109], v[186:187], 0, s[64:65]
	s_add_i32 m0, s2, s38
	s_nop 0
	global_load_lds_dwordx4 v[108:109], off
.LBB0_412:
	s_waitcnt lgkmcnt(4)
	v_mfma_f32_32x32x16_bf16 v[34:49], v[162:165], v[126:129], v[34:49]
	v_exp_f32_e32 v83, v83
	v_exp_f32_e32 v67, v67
	ds_read_b64_tr_b16 v[106:107], v227 offset:4096
	ds_read_b64_tr_b16 v[108:109], v227 offset:6144
	s_waitcnt lgkmcnt(4)
	v_mfma_f32_32x32x16_bf16 v[18:33], v[162:165], v[102:105], v[18:33]
	v_exp_f32_e32 v84, v84
	v_exp_f32_e32 v68, v68
	v_add_f32_e32 v111, v67, v66
	v_add_f32_e32 v110, v83, v82
	ds_read_b64_tr_b16 v[102:103], v227 offset:4608
	ds_read_b64_tr_b16 v[104:105], v227 offset:6656
	s_andn2_b64 vcc, exec, s[12:13]
	s_cbranch_vccnz .LBB0_414
	s_add_i32 s12, s2, s38
	v_lshl_add_u64 v[112:113], v[184:185], 0, s[64:65]
	s_add_i32 m0, s12, 0x2000
	s_nop 0
	global_load_lds_dwordx4 v[112:113], off

; #define SBAR() __builtin_amdgcn_sched_barrier(0)
; #define PIN(x) asm volatile("" : "+v"(x))
; template <int DK, bool NOMAX> ...
;     ...
;   float psa = 0.f, psb = 0.f;
;   SBAR();
; #pragma unroll
;   for (int d0 = 0; d0 < NS; ++d0) {
;     if (d0 == 0) { c0 = __builtin_amdgcn_mfma_f32_32x32x16_bf16(kf[0][0], qr[0], f32x16{}, 0, 0, 0); c1 = __builtin_amdgcn_mfma_f32_32x32x16_bf16(kf[0][1], qr[0], f32x16{}, 0, 0, 0); }
;     else { c0 = __builtin_amdgcn_mfma_f32_32x32x16_bf16(kf[d0 & 1][0], qr[d0], c0, 0, 0, 0); c1 = __builtin_amdgcn_mfma_f32_32x32x16_bf16(kf[d0 & 1][1], qr[d0], c1, 0, 0, 0); }
;     if (d0 + 2 < NS) KRD_(d0 & 1, d0 + 2);
;     if constexpr (NOMAX) { }
;     else {
; #pragma unroll
;     for (int r = d0 * RPS; r < (d0 + 1) * RPS; ++r) { p1[r] = __builtin_amdgcn_exp2f(p1[r]); psa += p0[r]; }
;     if (d0 > 0) {
; #pragma unroll
;       for (int r = (d0 - 1) * RPS; r < d0 * RPS; ++r) psb += p1[r]; } }
;     if constexpr (NOMAX) {
;       if (d0 == NS / 4 - 1) { PK4R(p0, 0, pa[0]); PIN(pa[0]); }
;       if (d0 == NS / 2 - 1) { PK4R(p0, 8, pa[1]); PIN(pa[1]); }
;       if (d0 == 3 * NS / 4 - 1) { PK4R(p1, 0, pa[2]); PIN(pa[2]); }
;       if (d0 == NS - 1) { PK4R(p1, 8, pa[3]); PIN(pa[3]); }
;     } else {
;     if (d0 == NS / 2 - 1) { PK4R(p0, 0, pa[0]); PIN(pa[0]); }
;     if (d0 == NS / 2) { PK4R(p0, 8, pa[1]); PIN(pa[1]); }
;     if (d0 == NS - 1) { PK4R(p1, 0, pa[2]); PIN(pa[2]); }
;     }
;     if (d0 == NS - 1) {
;       vl[0] = vtr(vp + v_rd_off(0, 0, 0)); vh[0] = vtr(vp + v_rd_off(0, 0, 1)); vl[1] = vtr(vp + v_rd_off(1, 0, 0)); vh[1] = vtr(vp + v_rd_off(1, 0, 1)); }
;     PIN(p1); PIN(psa); PIN(psb);
;     SBAR();
;   }
; template <int DK, bool NOMAX> ...
;     ...
; #pragma unroll
;   for (int i = 0; i < 16; ++i) {
;     if (i + 2 < 16) VRD_((i + 2) % 3, i + 2);
;     if (i == 1) { if (dk) __builtin_amdgcn_global_load_lds((const unsigned*)gk0, lk, 16, 0, 0); }
;     if (i == 3) { if constexpr (DK == 128) { if (dk) __builtin_amdgcn_global_load_lds((const unsigned*)gk1, (lds_up)((lds_cp)lk + 8192), 16, 0, 0); } }
;     if (i == 5) { if (dv) __builtin_amdgcn_global_load_lds((const unsigned*)gv0, lv, 16, 0, 0); }
;     if (i == 7) { if (dv) __builtin_amdgcn_global_load_lds((const unsigned*)gv1, (lds_up)((lds_cp)lv + 8192), 16, 0, 0); }
;     if (i == 12 || i == 13) { const int cb_ = ((i - 12) * 16 + hi * 8) * 2;
.LBB0_462:
	s_mov_b32 s17, s15
	s_mov_b32 s15, s8
	s_add_i32 s8, s18, 0xffffc000
	s_and_b32 s38, s8, 0xc000
	s_add_i32 s8, s38, 0
	v_add_u32_e32 v0, s15, v204
	s_waitcnt lgkmcnt(0)
	v_mfma_f32_32x32x16_bf16 v[114:129], v[102:105], v[158:161], 0
	v_add_u32_e32 v188, s8, v218
	ds_read_b128 v[184:187], v188
	ds_read_b128 v[188:191], v188 offset:8192
	v_mfma_f32_32x32x16_bf16 v[98:113], v[98:101], v[158:161], 0
	v_mfma_f32_32x32x16_bf16 v[114:129], v[166:169], v[154:157], v[114:129]
	v_mfma_f32_32x32x16_bf16 v[98:113], v[162:165], v[154:157], v[98:113]
	v_add_u32_e32 v162, s8, v219
	ds_read_b128 v[166:169], v162
	ds_read_b128 v[226:229], v162 offset:8192
	v_cvt_pk_bf16_f32 v162, v82, v83
	v_cvt_pk_bf16_f32 v163, v84, v85
	v_cvt_pk_bf16_f32 v164, v86, v87
	v_cvt_pk_bf16_f32 v165, v88, v89
	s_nop 0
	v_permlane32_swap_b32_e32 v162, v164
	v_permlane32_swap_b32_e32 v163, v165
	s_waitcnt lgkmcnt(3)
	v_mfma_f32_32x32x16_bf16 v[114:129], v[184:187], v[150:153], v[114:129]
	v_add_u32_e32 v86, s8, v220
	ds_read_b128 v[82:85], v86
	ds_read_b128 v[86:89], v86 offset:8192
	s_waitcnt lgkmcnt(4)
	v_mfma_f32_32x32x16_bf16 v[98:113], v[188:191], v[150:153], v[98:113]
	s_waitcnt lgkmcnt(3)
	v_mfma_f32_32x32x16_bf16 v[114:129], v[166:169], v[146:149], v[114:129]
	v_add_u32_e32 v184, s8, v221
	ds_read_b128 v[166:169], v184
	ds_read_b128 v[184:187], v184 offset:8192
	v_cvt_pk_bf16_f32 v90, v90, v91
	v_cvt_pk_bf16_f32 v91, v92, v93
	v_cvt_pk_bf16_f32 v92, v94, v95
	v_cvt_pk_bf16_f32 v93, v96, v97
	s_waitcnt lgkmcnt(4)
	v_mfma_f32_32x32x16_bf16 v[98:113], v[226:229], v[146:149], v[98:113]
	v_permlane32_swap_b32_e32 v90, v92
	v_permlane32_swap_b32_e32 v91, v93
	s_waitcnt lgkmcnt(3)
	v_mfma_f32_32x32x16_bf16 v[114:129], v[82:85], v[142:145], v[114:129]
	s_waitcnt lgkmcnt(2)
	v_mfma_f32_32x32x16_bf16 v[98:113], v[86:89], v[142:145], v[98:113]
	v_add_u32_e32 v86, s8, v222
	ds_read_b128 v[82:85], v86
	ds_read_b128 v[94:97], v86 offset:8192
	s_waitcnt lgkmcnt(3)
	v_mfma_f32_32x32x16_bf16 v[114:129], v[166:169], v[138:141], v[114:129]
	v_add_u32_e32 v86, s8, v223
	s_waitcnt lgkmcnt(2)
	v_mfma_f32_32x32x16_bf16 v[98:113], v[184:187], v[138:141], v[98:113]
	ds_read_b128 v[166:169], v86
	ds_read_b128 v[184:187], v86 offset:8192
	v_cvt_pk_bf16_f32 v86, v66, v67
	v_cvt_pk_bf16_f32 v87, v68, v69
	v_cvt_pk_bf16_f32 v88, v70, v71
	v_cvt_pk_bf16_f32 v89, v72, v73
	s_nop 0
	v_permlane32_swap_b32_e32 v86, v88
	v_permlane32_swap_b32_e32 v87, v89
	s_waitcnt lgkmcnt(3)
	v_mfma_f32_32x32x16_bf16 v[114:129], v[82:85], v[130:133], v[114:129]
	s_waitcnt lgkmcnt(2)
	v_mfma_f32_32x32x16_bf16 v[98:113], v[94:97], v[130:133], v[98:113]
	v_cvt_pk_bf16_f32 v82, v74, v75
	v_cvt_pk_bf16_f32 v83, v76, v77
	v_cvt_pk_bf16_f32 v84, v78, v79
	v_cvt_pk_bf16_f32 v85, v80, v81
	s_waitcnt lgkmcnt(1)
	v_mfma_f32_32x32x16_bf16 v[114:129], v[166:169], v[134:137], v[114:129]
	v_permlane32_swap_b32_e32 v82, v84
	v_permlane32_swap_b32_e32 v83, v85
	ds_read_b64_tr_b16 v[166:167], v0
	ds_read_b64_tr_b16 v[168:169], v0 offset:2048
	ds_read_b64_tr_b16 v[94:95], v0 offset:512
	ds_read_b64_tr_b16 v[96:97], v0 offset:2560
	s_waitcnt lgkmcnt(4)
	v_mfma_f32_32x32x16_bf16 v[98:113], v[184:187], v[134:137], v[98:113]
	s_cmp_lt_u32 s14, 61
	s_cselect_b64 s[10:11], -1, 0
	s_cmp_gt_u32 s14, 60
	s_cselect_b64 s[8:9], -1, 0
	s_add_i32 s19, s18, 0x8000
	s_and_b32 s12, s19, 0xc000
	ds_read_b64_tr_b16 v[70:71], v0 offset:1024
	ds_read_b64_tr_b16 v[72:73], v0 offset:3072
	s_waitcnt lgkmcnt(4)
	v_mfma_f32_32x32x16_bf16 v[50:65], v[162:165], v[166:169], v[50:65]
	v_exp_f32_e32 v114, v114
	s_nop 0
	v_exp_f32_e32 v98, v98
	ds_read_b64_tr_b16 v[66:67], v0 offset:1536
	ds_read_b64_tr_b16 v[68:69], v0 offset:3584
	s_and_b64 vcc, exec, s[8:9]
	v_lshl_add_u64 v[186:187], s[0:1], 0, v[182:183]
	s_cbranch_vccnz .LBB0_464
	v_lshl_add_u64 v[76:77], v[186:187], 0, s[50:51]
	s_add_i32 m0, s2, s12
	s_nop 0
	global_load_lds_dwordx4 v[76:77], off

; #define SBAR() __builtin_amdgcn_sched_barrier(0)
; #define PIN(x) asm volatile("" : "+v"(x))
; template <int DK, bool NOMAX> ...
;     ...
;   float psa = 0.f, psb = 0.f;
;   SBAR();
; #pragma unroll
;   for (int d0 = 0; d0 < NS; ++d0) {
;     if (d0 == 0) { c0 = __builtin_amdgcn_mfma_f32_32x32x16_bf16(kf[0][0], qr[0], f32x16{}, 0, 0, 0); c1 = __builtin_amdgcn_mfma_f32_32x32x16_bf16(kf[0][1], qr[0], f32x16{}, 0, 0, 0); }
;     else { c0 = __builtin_amdgcn_mfma_f32_32x32x16_bf16(kf[d0 & 1][0], qr[d0], c0, 0, 0, 0); c1 = __builtin_amdgcn_mfma_f32_32x32x16_bf16(kf[d0 & 1][1], qr[d0], c1, 0, 0, 0); }
;     if (d0 + 2 < NS) KRD_(d0 & 1, d0 + 2);
;     if constexpr (NOMAX) { }
;     else {
; #pragma unroll
;     for (int r = d0 * RPS; r < (d0 + 1) * RPS; ++r) { p1[r] = __builtin_amdgcn_exp2f(p1[r]); psa += p0[r]; }
;     if (d0 > 0) {
; #pragma unroll
;       for (int r = (d0 - 1) * RPS; r < d0 * RPS; ++r) psb += p1[r]; } }
;     if constexpr (NOMAX) {
;       if (d0 == NS / 4 - 1) { PK4R(p0, 0, pa[0]); PIN(pa[0]); }
;       if (d0 == NS / 2 - 1) { PK4R(p0, 8, pa[1]); PIN(pa[1]); }
;       if (d0 == 3 * NS / 4 - 1) { PK4R(p1, 0, pa[2]); PIN(pa[2]); }
;       if (d0 == NS - 1) { PK4R(p1, 8, pa[3]); PIN(pa[3]); }
;     } else {
;     if (d0 == NS / 2 - 1) { PK4R(p0, 0, pa[0]); PIN(pa[0]); }
;     if (d0 == NS / 2) { PK4R(p0, 8, pa[1]); PIN(pa[1]); }
;     if (d0 == NS - 1) { PK4R(p1, 0, pa[2]); PIN(pa[2]); }
;     }
;     if (d0 == NS - 1) {
;       vl[0] = vtr(vp + v_rd_off(0, 0, 0)); vh[0] = vtr(vp + v_rd_off(0, 0, 1)); vl[1] = vtr(vp + v_rd_off(1, 0, 0)); vh[1] = vtr(vp + v_rd_off(1, 0, 1)); }
;     PIN(p1); PIN(psa); PIN(psb);
;     SBAR();
;   }
; template <int DK, bool NOMAX> ...
;     ...
; #pragma unroll
;   for (int i = 0; i < 16; ++i) {
;     if (i + 2 < 16) VRD_((i + 2) % 3, i + 2);
;     if (i == 1) { if (dk) __builtin_amdgcn_global_load_lds((const unsigned*)gk0, lk, 16, 0, 0); }
;     if (i == 3) { if constexpr (DK == 128) { if (dk) __builtin_amdgcn_global_load_lds((const unsigned*)gk1, (lds_up)((lds_cp)lk + 8192), 16, 0, 0); } }
;     if (i == 5) { if (dv) __builtin_amdgcn_global_load_lds((const unsigned*)gv0, lv, 16, 0, 0); }
;     if (i == 7) { if (dv) __builtin_amdgcn_global_load_lds((const unsigned*)gv1, (lds_up)((lds_cp)lv + 8192), 16, 0, 0); }
;     if (i == 12 || i == 13) { const int cb_ = ((i - 12) * 16 + hi * 8) * 2;
.LBB0_470:
	v_add_u32_e32 v227, s17, v204
	v_mfma_f32_32x32x16_bf16 v[82:97], v[66:69], v[158:161], 0
	v_add_u32_e32 v232, s12, v218
	ds_read_b128 v[228:231], v232
	ds_read_b128 v[232:235], v232 offset:8192
	v_mfma_f32_32x32x16_bf16 v[66:81], v[70:73], v[158:161], 0
	v_mfma_f32_32x32x16_bf16 v[82:97], v[162:165], v[154:157], v[82:97]
	v_add_u32_e32 v162, s12, v219
	v_mfma_f32_32x32x16_bf16 v[66:81], v[166:169], v[154:157], v[66:81]
	ds_read_b128 v[166:169], v162
	ds_read_b128 v[236:239], v162 offset:8192
	v_cvt_pk_bf16_f32 v162, v114, v115
	v_cvt_pk_bf16_f32 v163, v116, v117
	v_cvt_pk_bf16_f32 v164, v118, v119
	v_cvt_pk_bf16_f32 v165, v120, v121
	s_nop 0
	v_permlane32_swap_b32_e32 v162, v164
	v_permlane32_swap_b32_e32 v163, v165
	s_waitcnt lgkmcnt(3)
	v_mfma_f32_32x32x16_bf16 v[82:97], v[228:231], v[150:153], v[82:97]
	v_add_u32_e32 v118, s12, v220
	ds_read_b128 v[114:117], v118
	ds_read_b128 v[118:121], v118 offset:8192
	s_waitcnt lgkmcnt(4)
	v_mfma_f32_32x32x16_bf16 v[66:81], v[232:235], v[150:153], v[66:81]
	s_waitcnt lgkmcnt(3)
	v_mfma_f32_32x32x16_bf16 v[82:97], v[166:169], v[146:149], v[82:97]
	v_add_u32_e32 v228, s12, v221
	ds_read_b128 v[166:169], v228
	ds_read_b128 v[228:231], v228 offset:8192
	v_cvt_pk_bf16_f32 v122, v122, v123
	v_cvt_pk_bf16_f32 v123, v124, v125
	v_cvt_pk_bf16_f32 v124, v126, v127
	v_cvt_pk_bf16_f32 v125, v128, v129
	s_waitcnt lgkmcnt(4)
	v_mfma_f32_32x32x16_bf16 v[66:81], v[236:239], v[146:149], v[66:81]
	v_permlane32_swap_b32_e32 v122, v124
	v_permlane32_swap_b32_e32 v123, v125
	s_waitcnt lgkmcnt(3)
	v_mfma_f32_32x32x16_bf16 v[82:97], v[114:117], v[142:145], v[82:97]
	s_waitcnt lgkmcnt(2)
	v_mfma_f32_32x32x16_bf16 v[66:81], v[118:121], v[142:145], v[66:81]
	v_add_u32_e32 v118, s12, v222
	ds_read_b128 v[114:117], v118
	ds_read_b128 v[126:129], v118 offset:8192
	s_waitcnt lgkmcnt(3)
	v_mfma_f32_32x32x16_bf16 v[82:97], v[166:169], v[138:141], v[82:97]
	v_add_u32_e32 v118, s12, v223
	s_waitcnt lgkmcnt(2)
	v_mfma_f32_32x32x16_bf16 v[66:81], v[228:231], v[138:141], v[66:81]
	ds_read_b128 v[166:169], v118
	ds_read_b128 v[228:231], v118 offset:8192
	v_cvt_pk_bf16_f32 v118, v98, v99
	v_cvt_pk_bf16_f32 v119, v100, v101
	v_cvt_pk_bf16_f32 v120, v102, v103
	v_cvt_pk_bf16_f32 v121, v104, v105
	s_nop 0
	v_permlane32_swap_b32_e32 v118, v120
	v_permlane32_swap_b32_e32 v119, v121
	s_waitcnt lgkmcnt(3)
	v_mfma_f32_32x32x16_bf16 v[82:97], v[114:117], v[130:133], v[82:97]
	s_waitcnt lgkmcnt(2)
	v_mfma_f32_32x32x16_bf16 v[66:81], v[126:129], v[130:133], v[66:81]
	v_cvt_pk_bf16_f32 v114, v106, v107
	v_cvt_pk_bf16_f32 v115, v108, v109
	v_cvt_pk_bf16_f32 v116, v110, v111
	v_cvt_pk_bf16_f32 v117, v112, v113
	s_waitcnt lgkmcnt(1)
	v_mfma_f32_32x32x16_bf16 v[82:97], v[166:169], v[134:137], v[82:97]
	v_permlane32_swap_b32_e32 v114, v116
	v_permlane32_swap_b32_e32 v115, v117
	ds_read_b64_tr_b16 v[166:167], v227
	ds_read_b64_tr_b16 v[168:169], v227 offset:2048
	ds_read_b64_tr_b16 v[126:127], v227 offset:512
	ds_read_b64_tr_b16 v[128:129], v227 offset:2560
	s_waitcnt lgkmcnt(4)
	v_mfma_f32_32x32x16_bf16 v[66:81], v[228:231], v[134:137], v[66:81]
	s_cmp_lt_u32 s14, 60
	s_cselect_b64 s[12:13], -1, 0
	s_cmp_gt_u32 s14, 59
	s_cselect_b64 s[10:11], -1, 0
	ds_read_b64_tr_b16 v[102:103], v227 offset:1024
	ds_read_b64_tr_b16 v[104:105], v227 offset:3072
	s_waitcnt lgkmcnt(4)
	v_mfma_f32_32x32x16_bf16 v[50:65], v[162:165], v[166:169], v[50:65]
	v_exp_f32_e32 v82, v82
	s_nop 2
	v_exp_f32_e32 v66, v66
	ds_read_b64_tr_b16 v[98:99], v227 offset:1536
	ds_read_b64_tr_b16 v[100:101], v227 offset:3584
	s_and_b64 vcc, exec, s[10:11]
	s_cbranch_vccnz .LBB0_472
	v_lshl_add_u64 v[108:109], v[186:187], 0, s[64:65]
	s_add_i32 m0, s2, s38
	s_nop 0
	global_load_lds_dwordx4 v[108:109], off
